# selection: the two top-256 threshold searches rewritten by hand (single count site, scalar bracket state, tracked count at hi so no extra final pass)
# speedup vs baseline: 1.0592x; 1.0048x over previous
; __device__ __forceinline__ int count_ge(const unsigned (&u)[64], unsigned cand, int nblk) {
;     int c0 = 0, c1 = 0;
;     const unsigned ts = __builtin_amdgcn_readfirstlane(cand);
; #pragma unroll
;     for (int B = 0; B < 2; ++B) {
;         if (B < nblk) {
; #pragma unroll
;             for (int i = 0; i < 32; i += 4) CNT4(c0, c1, ts, u[B * 32 + i], u[B * 32 + i + 1], u[B * 32 + i + 2], u[B * 32 + i + 3]);
;         }
;     }
;     return wave_isum(c0 + c1);
; __device__ __forceinline__ void select_query(const unsigned (&u)[64], unsigned vmax, int q, int b, int lane, unsigned* MASKb) {
;     ...
;     if (n > 256) {
;         const unsigned kmax = wave_umax(vmax);
;         const unsigned K0 = 0x80000000u;
;         bool exact = false, done = false;
;         unsigned lo = 0u, hi = 0u; float Llo = 1.f, Lhi = 1.f;
;         const float L256 = 8.0028150156f;
;         const int cpos = count_ge(u, K0 + 1u, nblk);
;         if (cpos == 256) { T = K0 + 1u; exact = true; done = true; }
;         else if (cpos > 256) { lo = K0 + 1u; Llo = __log2f((float)cpos) - L256; hi = kmax + 1u; Lhi = L256 + 1.f; }
.LBB0_130:
	v_add_u32_e32 v0, 0x800, v106
	v_ashrrev_i32_e32 v190, 11, v0
	s_mov_b64 s[8:9], exec
	v_mov_b32_e32 v192, 0
	v_mov_b32_e32 v193, 0
	v_mov_b32_e32 v191, 0
	s_cmpk_gt_i32 s75, 0xff
	s_cbranch_scc0 .Lsqa_done
	s_add_i32 s25, s75, 0x800
	s_lshr_b32 s25, s25, 11
	v_max_u32_dpp v191, v185, v185 row_shr:1 row_mask:0xf bank_mask:0xf bound_ctrl:1
	s_nop 1
	v_max_u32_dpp v191, v191, v191 row_shr:2 row_mask:0xf bank_mask:0xf bound_ctrl:1
	s_nop 1
	v_max_u32_dpp v191, v191, v191 row_shr:4 row_mask:0xf bank_mask:0xf bound_ctrl:1
	s_nop 1
	v_max_u32_dpp v191, v191, v191 row_shr:8 row_mask:0xf bank_mask:0xf bound_ctrl:1
	s_nop 1
	v_max_u32_dpp v191, v191, v191 row_bcast:15 row_mask:0xa bank_mask:0xf
	s_nop 1
	v_max_u32_dpp v191, v191, v191 row_bcast:31 row_mask:0xc bank_mask:0xf
	s_nop 0
	v_readlane_b32 s19, v191, 63
	s_mov_b32 s21, 0
	s_mov_b32 s14, 0x80000001
.Lsqa_count:
	v_mov_b32_e32 v0, 0
	v_mov_b32_e32 v34, 0
	v_cmp_le_u32_e64 s[4:5], s14, v138
	v_cmp_le_u32_e64 s[6:7], s14, v140
	v_cmp_le_u32_e64 s[10:11], s14, v139
	v_cmp_le_u32_e64 s[26:27], s14, v141
	v_addc_co_u32_e64 v0, s[28:29], 0, v0, s[4:5]
	v_addc_co_u32_e64 v34, s[30:31], 0, v34, s[6:7]
	v_addc_co_u32_e64 v0, s[28:29], 0, v0, s[10:11]
	v_addc_co_u32_e64 v34, s[30:31], 0, v34, s[26:27]
	v_cmp_le_u32_e64 s[4:5], s14, v142
	v_cmp_le_u32_e64 s[6:7], s14, v146
	v_cmp_le_u32_e64 s[10:11], s14, v143
	v_cmp_le_u32_e64 s[26:27], s14, v147
	v_addc_co_u32_e64 v0, s[28:29], 0, v0, s[4:5]
	v_addc_co_u32_e64 v34, s[30:31], 0, v34, s[6:7]
	v_addc_co_u32_e64 v0, s[28:29], 0, v0, s[10:11]
	v_addc_co_u32_e64 v34, s[30:31], 0, v34, s[26:27]
	v_cmp_le_u32_e64 s[4:5], s14, v144
	v_cmp_le_u32_e64 s[6:7], s14, v148
	v_cmp_le_u32_e64 s[10:11], s14, v145
	v_cmp_le_u32_e64 s[26:27], s14, v149
	v_addc_co_u32_e64 v0, s[28:29], 0, v0, s[4:5]
	v_addc_co_u32_e64 v34, s[30:31], 0, v34, s[6:7]
	v_addc_co_u32_e64 v0, s[28:29], 0, v0, s[10:11]
	v_addc_co_u32_e64 v34, s[30:31], 0, v34, s[26:27]
	v_cmp_le_u32_e64 s[4:5], s14, v150
	v_cmp_le_u32_e64 s[6:7], s14, v152
	v_cmp_le_u32_e64 s[10:11], s14, v151
	v_cmp_le_u32_e64 s[26:27], s14, v154
	v_addc_co_u32_e64 v0, s[28:29], 0, v0, s[4:5]
	v_addc_co_u32_e64 v34, s[30:31], 0, v34, s[6:7]
	v_addc_co_u32_e64 v0, s[28:29], 0, v0, s[10:11]
	v_addc_co_u32_e64 v34, s[30:31], 0, v34, s[26:27]
	v_cmp_le_u32_e64 s[4:5], s14, v153
	v_cmp_le_u32_e64 s[6:7], s14, v156
	v_cmp_le_u32_e64 s[10:11], s14, v155
	v_cmp_le_u32_e64 s[26:27], s14, v157
	v_addc_co_u32_e64 v0, s[28:29], 0, v0, s[4:5]
	v_addc_co_u32_e64 v34, s[30:31], 0, v34, s[6:7]
	v_addc_co_u32_e64 v0, s[28:29], 0, v0, s[10:11]
	v_addc_co_u32_e64 v34, s[30:31], 0, v34, s[26:27]
	v_cmp_le_u32_e64 s[4:5], s14, v158
	v_cmp_le_u32_e64 s[6:7], s14, v160
	v_cmp_le_u32_e64 s[10:11], s14, v159
	v_cmp_le_u32_e64 s[26:27], s14, v161
	v_addc_co_u32_e64 v0, s[28:29], 0, v0, s[4:5]
	v_addc_co_u32_e64 v34, s[30:31], 0, v34, s[6:7]
	v_addc_co_u32_e64 v0, s[28:29], 0, v0, s[10:11]
	v_addc_co_u32_e64 v34, s[30:31], 0, v34, s[26:27]
	v_cmp_le_u32_e64 s[4:5], s14, v167
	v_cmp_le_u32_e64 s[6:7], s14, v169
	v_cmp_le_u32_e64 s[10:11], s14, v168
	v_cmp_le_u32_e64 s[26:27], s14, v170
	v_addc_co_u32_e64 v0, s[28:29], 0, v0, s[4:5]
	v_addc_co_u32_e64 v34, s[30:31], 0, v34, s[6:7]
	v_addc_co_u32_e64 v0, s[28:29], 0, v0, s[10:11]
	v_addc_co_u32_e64 v34, s[30:31], 0, v34, s[26:27]
	v_cmp_le_u32_e64 s[4:5], s14, v173
	v_cmp_le_u32_e64 s[6:7], s14, v174
	v_cmp_le_u32_e64 s[10:11], s14, v175
	v_cmp_le_u32_e64 s[26:27], s14, v176
	v_addc_co_u32_e64 v0, s[28:29], 0, v0, s[4:5]
	v_addc_co_u32_e64 v34, s[30:31], 0, v34, s[6:7]
	v_addc_co_u32_e64 v0, s[28:29], 0, v0, s[10:11]
	v_addc_co_u32_e64 v34, s[30:31], 0, v34, s[26:27]
	s_cmp_lt_u32 s25, 2
	s_cbranch_scc1 .Lsqa_red
	v_cmp_le_u32_e64 s[4:5], s14, v76
	v_cmp_le_u32_e64 s[6:7], s14, v78
	v_cmp_le_u32_e64 s[10:11], s14, v77
	v_cmp_le_u32_e64 s[26:27], s14, v79
	v_addc_co_u32_e64 v0, s[28:29], 0, v0, s[4:5]
	v_addc_co_u32_e64 v34, s[30:31], 0, v34, s[6:7]
	v_addc_co_u32_e64 v0, s[28:29], 0, v0, s[10:11]
	v_addc_co_u32_e64 v34, s[30:31], 0, v34, s[26:27]
	v_cmp_le_u32_e64 s[4:5], s14, v80
	v_cmp_le_u32_e64 s[6:7], s14, v84
	v_cmp_le_u32_e64 s[10:11], s14, v81
	v_cmp_le_u32_e64 s[26:27], s14, v85
	v_addc_co_u32_e64 v0, s[28:29], 0, v0, s[4:5]
	v_addc_co_u32_e64 v34, s[30:31], 0, v34, s[6:7]
	v_addc_co_u32_e64 v0, s[28:29], 0, v0, s[10:11]
	v_addc_co_u32_e64 v34, s[30:31], 0, v34, s[26:27]
	v_cmp_le_u32_e64 s[4:5], s14, v82
	v_cmp_le_u32_e64 s[6:7], s14, v86
	v_cmp_le_u32_e64 s[10:11], s14, v83
	v_cmp_le_u32_e64 s[26:27], s14, v87
	v_addc_co_u32_e64 v0, s[28:29], 0, v0, s[4:5]
	v_addc_co_u32_e64 v34, s[30:31], 0, v34, s[6:7]
	v_addc_co_u32_e64 v0, s[28:29], 0, v0, s[10:11]
	v_addc_co_u32_e64 v34, s[30:31], 0, v34, s[26:27]
	v_cmp_le_u32_e64 s[4:5], s14, v89
	v_cmp_le_u32_e64 s[6:7], s14, v91
	v_cmp_le_u32_e64 s[10:11], s14, v90
	v_cmp_le_u32_e64 s[26:27], s14, v93
	v_addc_co_u32_e64 v0, s[28:29], 0, v0, s[4:5]
	v_addc_co_u32_e64 v34, s[30:31], 0, v34, s[6:7]
	v_addc_co_u32_e64 v0, s[28:29], 0, v0, s[10:11]
	v_addc_co_u32_e64 v34, s[30:31], 0, v34, s[26:27]
	v_cmp_le_u32_e64 s[4:5], s14, v92
	v_cmp_le_u32_e64 s[6:7], s14, v95
	v_cmp_le_u32_e64 s[10:11], s14, v94
	v_cmp_le_u32_e64 s[26:27], s14, v96
	v_addc_co_u32_e64 v0, s[28:29], 0, v0, s[4:5]
	v_addc_co_u32_e64 v34, s[30:31], 0, v34, s[6:7]
	v_addc_co_u32_e64 v0, s[28:29], 0, v0, s[10:11]
	v_addc_co_u32_e64 v34, s[30:31], 0, v34, s[26:27]
	v_cmp_le_u32_e64 s[4:5], s14, v97
	v_cmp_le_u32_e64 s[6:7], s14, v172
	v_cmp_le_u32_e64 s[10:11], s14, v171
	v_cmp_le_u32_e64 s[26:27], s14, v178
	v_addc_co_u32_e64 v0, s[28:29], 0, v0, s[4:5]
	v_addc_co_u32_e64 v34, s[30:31], 0, v34, s[6:7]
	v_addc_co_u32_e64 v0, s[28:29], 0, v0, s[10:11]
	v_addc_co_u32_e64 v34, s[30:31], 0, v34, s[26:27]
	v_cmp_le_u32_e64 s[4:5], s14, v180
	v_cmp_le_u32_e64 s[6:7], s14, v183
	v_cmp_le_u32_e64 s[10:11], s14, v182
	v_cmp_le_u32_e64 s[26:27], s14, v184
	v_addc_co_u32_e64 v0, s[28:29], 0, v0, s[4:5]
	v_addc_co_u32_e64 v34, s[30:31], 0, v34, s[6:7]
	v_addc_co_u32_e64 v0, s[28:29], 0, v0, s[10:11]
	v_addc_co_u32_e64 v34, s[30:31], 0, v34, s[26:27]
	v_cmp_le_u32_e64 s[4:5], s14, v186
	v_cmp_le_u32_e64 s[6:7], s14, v187
	v_cmp_le_u32_e64 s[10:11], s14, v188
	v_cmp_le_u32_e64 s[26:27], s14, v189
	v_addc_co_u32_e64 v0, s[28:29], 0, v0, s[4:5]
	v_addc_co_u32_e64 v34, s[30:31], 0, v34, s[6:7]
	v_addc_co_u32_e64 v0, s[28:29], 0, v0, s[10:11]
	v_addc_co_u32_e64 v34, s[30:31], 0, v34, s[26:27]
; __device__ __forceinline__ void select_query(const unsigned (&u)[64], unsigned vmax, int q, int b, int lane, unsigned* MASKb) {
;     ...
;         const unsigned kmax = wave_umax(vmax);
;         const unsigned K0 = 0x80000000u;
;         bool exact = false, done = false;
;         unsigned lo = 0u, hi = 0u; float Llo = 1.f, Lhi = 1.f;
;         const float L256 = 8.0028150156f;
;         const int cpos = count_ge(u, K0 + 1u, nblk);
;         if (cpos == 256) { T = K0 + 1u; exact = true; done = true; }
;         else if (cpos > 256) { lo = K0 + 1u; Llo = __log2f((float)cpos) - L256; hi = kmax + 1u; Lhi = L256 + 1.f; }
;         else {
;             const int c0 = count_ge(u, K0, nblk);
;             if (c0 >= 256) { T = K0; exact = (c0 == 256); done = true; }
;             else {
;                 unsigned vmin = 0xffffffffu;
; #pragma unroll
;                 for (int i = 0; i < 64; ++i) vmin = min(vmin, u[i] - 1u);
;                 lo = ~wave_umax(~vmin) + 1u; Llo = __log2f((float)n) - L256; hi = K0; Lhi = L256 - __log2f(fmaxf((float)c0, 0.5f));
;             }
;         }
.Lsqa_red:
	v_add_u32_e32 v0, v0, v34
	s_nop 1
	v_add_u32_dpp v0, v0, v0 row_shr:1 row_mask:0xf bank_mask:0xf bound_ctrl:1
	s_nop 1
	v_add_u32_dpp v0, v0, v0 row_shr:2 row_mask:0xf bank_mask:0xf bound_ctrl:1
	s_nop 1
	v_add_u32_dpp v0, v0, v0 row_shr:4 row_mask:0xf bank_mask:0xf bound_ctrl:1
	s_nop 1
	v_add_u32_dpp v0, v0, v0 row_shr:8 row_mask:0xf bank_mask:0xf bound_ctrl:1
	s_nop 1
	v_add_u32_dpp v0, v0, v0 row_bcast:15 row_mask:0xa bank_mask:0xf
	s_nop 1
	v_add_u32_dpp v0, v0, v0 row_bcast:31 row_mask:0xc bank_mask:0xf
	s_nop 0
	v_readlane_b32 s24, v0, 63
	s_cmp_eq_u32 s21, 2
	s_cbranch_scc1 .Lsqa_st2
	s_cmp_eq_u32 s21, 1
	s_cbranch_scc1 .Lsqa_st1
	s_cmpk_eq_i32 s24, 0x100
	s_cbranch_scc1 .Lsqa_exact
	s_cmpk_gt_i32 s24, 0x100
	s_cbranch_scc0 .Lsqa_s0lt
	s_mov_b32 s13, 0x80000001
	s_add_i32 s12, s19, 1
	s_mov_b32 s15, 0
	v_cvt_f32_u32_e32 v35, s24
	v_log_f32_e32 v35, v35
	v_mov_b32_e32 v36, 0x41100b88
	v_add_f32_e32 v35, 0xc1000b88, v35
	s_mov_b32 s22, 0
	s_mov_b32 s23, 0
	s_mov_b32 s21, 2
	s_branch .Lsqa_next
.Lsqa_s0lt:
	s_mov_b32 s18, s24
	s_mov_b32 s14, 0x80000000
	s_mov_b32 s21, 1
	s_branch .Lsqa_count
.Lsqa_st1:
	s_cmpk_eq_i32 s24, 0x100
	s_cbranch_scc1 .Lsqa_exact
	s_cmpk_gt_i32 s24, 0x100
	s_cbranch_scc0 .Lsqa_s1lt
	s_mov_b32 s26, 0x80000000
	s_mov_b32 s27, 0x80000000
	s_sub_i32 s28, 0x100, s18
	s_branch .Lsqa_fin
.Lsqa_s1lt:
	v_mov_b32_e32 v191, -1
	v_add_u32_e32 v0, -1, v138
	v_min_u32_e32 v191, v191, v0
	v_add_u32_e32 v0, -1, v140
	v_min_u32_e32 v191, v191, v0
	v_add_u32_e32 v0, -1, v139
	v_min_u32_e32 v191, v191, v0
	v_add_u32_e32 v0, -1, v141
	v_min_u32_e32 v191, v191, v0
	v_add_u32_e32 v0, -1, v142
	v_min_u32_e32 v191, v191, v0
	v_add_u32_e32 v0, -1, v146
	v_min_u32_e32 v191, v191, v0
	v_add_u32_e32 v0, -1, v143
	v_min_u32_e32 v191, v191, v0
	v_add_u32_e32 v0, -1, v147
	v_min_u32_e32 v191, v191, v0
	v_add_u32_e32 v0, -1, v144
	v_min_u32_e32 v191, v191, v0
	v_add_u32_e32 v0, -1, v148
	v_min_u32_e32 v191, v191, v0
	v_add_u32_e32 v0, -1, v145
	v_min_u32_e32 v191, v191, v0
	v_add_u32_e32 v0, -1, v149
	v_min_u32_e32 v191, v191, v0
	v_add_u32_e32 v0, -1, v150
	v_min_u32_e32 v191, v191, v0
	v_add_u32_e32 v0, -1, v152
	v_min_u32_e32 v191, v191, v0
	v_add_u32_e32 v0, -1, v151
	v_min_u32_e32 v191, v191, v0
	v_add_u32_e32 v0, -1, v154
	v_min_u32_e32 v191, v191, v0
	v_add_u32_e32 v0, -1, v153
	v_min_u32_e32 v191, v191, v0
	v_add_u32_e32 v0, -1, v156
	v_min_u32_e32 v191, v191, v0
	v_add_u32_e32 v0, -1, v155
	v_min_u32_e32 v191, v191, v0
	v_add_u32_e32 v0, -1, v157
	v_min_u32_e32 v191, v191, v0
	v_add_u32_e32 v0, -1, v158
	v_min_u32_e32 v191, v191, v0
	v_add_u32_e32 v0, -1, v160
	v_min_u32_e32 v191, v191, v0
	v_add_u32_e32 v0, -1, v159
	v_min_u32_e32 v191, v191, v0
	v_add_u32_e32 v0, -1, v161
	v_min_u32_e32 v191, v191, v0
	v_add_u32_e32 v0, -1, v167
	v_min_u32_e32 v191, v191, v0
	v_add_u32_e32 v0, -1, v169
	v_min_u32_e32 v191, v191, v0
	v_add_u32_e32 v0, -1, v168
	v_min_u32_e32 v191, v191, v0
	v_add_u32_e32 v0, -1, v170
	v_min_u32_e32 v191, v191, v0
	v_add_u32_e32 v0, -1, v173
	v_min_u32_e32 v191, v191, v0
	v_add_u32_e32 v0, -1, v174
	v_min_u32_e32 v191, v191, v0
	v_add_u32_e32 v0, -1, v175
	v_min_u32_e32 v191, v191, v0
	v_add_u32_e32 v0, -1, v176
	v_min_u32_e32 v191, v191, v0
	v_add_u32_e32 v0, -1, v76
	v_min_u32_e32 v191, v191, v0
	v_add_u32_e32 v0, -1, v78
	v_min_u32_e32 v191, v191, v0
	v_add_u32_e32 v0, -1, v77
	v_min_u32_e32 v191, v191, v0
	v_add_u32_e32 v0, -1, v79
	v_min_u32_e32 v191, v191, v0
	v_add_u32_e32 v0, -1, v80
	v_min_u32_e32 v191, v191, v0
	v_add_u32_e32 v0, -1, v84
	v_min_u32_e32 v191, v191, v0
	v_add_u32_e32 v0, -1, v81
	v_min_u32_e32 v191, v191, v0
	v_add_u32_e32 v0, -1, v85
	v_min_u32_e32 v191, v191, v0
	v_add_u32_e32 v0, -1, v82
	v_min_u32_e32 v191, v191, v0
	v_add_u32_e32 v0, -1, v86
	v_min_u32_e32 v191, v191, v0
	v_add_u32_e32 v0, -1, v83
	v_min_u32_e32 v191, v191, v0
	v_add_u32_e32 v0, -1, v87
	v_min_u32_e32 v191, v191, v0
	v_add_u32_e32 v0, -1, v89
	v_min_u32_e32 v191, v191, v0
	v_add_u32_e32 v0, -1, v91
	v_min_u32_e32 v191, v191, v0
	v_add_u32_e32 v0, -1, v90
	v_min_u32_e32 v191, v191, v0
	v_add_u32_e32 v0, -1, v93
	v_min_u32_e32 v191, v191, v0
	v_add_u32_e32 v0, -1, v92
	v_min_u32_e32 v191, v191, v0
	v_add_u32_e32 v0, -1, v95
	v_min_u32_e32 v191, v191, v0
	v_add_u32_e32 v0, -1, v94
	v_min_u32_e32 v191, v191, v0
	v_add_u32_e32 v0, -1, v96
	v_min_u32_e32 v191, v191, v0
	v_add_u32_e32 v0, -1, v97
	v_min_u32_e32 v191, v191, v0
	v_add_u32_e32 v0, -1, v172
	v_min_u32_e32 v191, v191, v0
	v_add_u32_e32 v0, -1, v171
	v_min_u32_e32 v191, v191, v0
	v_add_u32_e32 v0, -1, v178
	v_min_u32_e32 v191, v191, v0
	v_add_u32_e32 v0, -1, v180
	v_min_u32_e32 v191, v191, v0
	v_add_u32_e32 v0, -1, v183
	v_min_u32_e32 v191, v191, v0
	v_add_u32_e32 v0, -1, v182
	v_min_u32_e32 v191, v191, v0
	v_add_u32_e32 v0, -1, v184
	v_min_u32_e32 v191, v191, v0
	v_add_u32_e32 v0, -1, v186
	v_min_u32_e32 v191, v191, v0
	v_add_u32_e32 v0, -1, v187
	v_min_u32_e32 v191, v191, v0
	v_add_u32_e32 v0, -1, v188
	v_min_u32_e32 v191, v191, v0
	v_add_u32_e32 v0, -1, v189
	v_min_u32_e32 v191, v191, v0
	v_not_b32_e32 v191, v191
	s_nop 1
	v_max_u32_dpp v191, v191, v191 row_shr:1 row_mask:0xf bank_mask:0xf bound_ctrl:1
	s_nop 1
	v_max_u32_dpp v191, v191, v191 row_shr:2 row_mask:0xf bank_mask:0xf bound_ctrl:1
	s_nop 1
	v_max_u32_dpp v191, v191, v191 row_shr:4 row_mask:0xf bank_mask:0xf bound_ctrl:1
	s_nop 1
	v_max_u32_dpp v191, v191, v191 row_shr:8 row_mask:0xf bank_mask:0xf bound_ctrl:1
	s_nop 1
	v_max_u32_dpp v191, v191, v191 row_bcast:15 row_mask:0xa bank_mask:0xf
	s_nop 1
	v_max_u32_dpp v191, v191, v191 row_bcast:31 row_mask:0xc bank_mask:0xf
	s_nop 0
	v_readlane_b32 s26, v191, 63
	s_sub_i32 s13, 0, s26
	s_mov_b32 s12, 0x80000000
	s_mov_b32 s15, s24
	s_add_i32 s26, s75, 1
	v_cvt_f32_u32_e32 v35, s26
	v_log_f32_e32 v35, v35
	v_cvt_f32_u32_e32 v36, s24
	v_max_f32_e32 v36, 0.5, v36
	v_log_f32_e32 v36, v36
	v_add_f32_e32 v35, 0xc1000b88, v35
	v_sub_f32_e32 v36, 0x41000b88, v36
	s_mov_b32 s22, 0
	s_mov_b32 s23, 0
	s_mov_b32 s21, 2
	s_branch .Lsqa_next
; __device__ __forceinline__ float keyval(unsigned k) { return __uint_as_float((k & 0x80000000u) ? (k ^ 0x80000000u) : ~k); }
; __device__ __forceinline__ unsigned valkey(float f) { const unsigned b = __float_as_uint(f); return b ^ ((unsigned)((int)b >> 31) | 0x80000000u); }
; __device__ __forceinline__ void select_query(const unsigned (&u)[64], unsigned vmax, int q, int b, int lane, unsigned* MASKb) {
;     ...
;         int it = 0, last = 0;
;         while (!done) {
;             if (hi - lo <= 1u) { T = lo; exact = false; break; }
;             const float vlo = keyval(lo), vhi = keyval(hi);
;             const float frac = (it >= 9 && (it & 1)) ? 0.5f : Llo * __builtin_amdgcn_rcpf(Llo + Lhi);
;             unsigned mid = valkey(vlo + frac * (vhi - vlo));
;             if (mid <= lo) mid = lo + 1u;
;             if (mid >= hi) mid = hi - 1u;
;             mid = __builtin_amdgcn_readfirstlane(mid);
;             const int c = count_ge(u, mid, nblk);
;             if (c == 256) { T = mid; exact = true; break; }
;             if (c > 256) { lo = mid; Llo = __log2f((float)c) - L256; if (last == 1) Lhi *= 0.5f; last = 1; }
;             else { hi = mid; Lhi = L256 - __log2f(fmaxf((float)c, 0.5f)); if (last == 2) Llo *= 0.5f; last = 2; }
;             ++it;
;         }
;         if (exact) TG = T - 1u; else { TG = T; rrem = 256 - count_ge(u, T + 1u, nblk); }
;     ...
;     int tbase = 0;
; #pragma unroll
;     for (int B = 0; B < 2; ++B) {
;         if (B < nblk) {
;             unsigned w = 0u; const unsigned tgs = __builtin_amdgcn_readfirstlane(TG);
; #pragma unroll
;             for (int e = 31; e >= 3; e -= 4) BIT4(w, tgs, u[B * 32 + e], u[B * 32 + e - 1], u[B * 32 + e - 2], u[B * 32 + e - 3]);
.Lsqa_st2:
	s_cmpk_eq_i32 s24, 0x100
	s_cbranch_scc1 .Lsqa_exact
	s_cmpk_gt_i32 s24, 0x100
	s_cbranch_scc0 .Lsqa_s2lt
	s_mov_b32 s13, s14
	v_cvt_f32_u32_e32 v35, s24
	v_log_f32_e32 v35, v35
	s_cmp_lg_u32 s23, 1
	s_cbranch_scc1 .Lsqa_s2a
	v_mul_f32_e32 v36, 0.5, v36
.Lsqa_s2a:
	v_add_f32_e32 v35, 0xc1000b88, v35
	s_mov_b32 s23, 1
	s_add_i32 s22, s22, 1
	s_branch .Lsqa_next
.Lsqa_s2lt:
	s_mov_b32 s12, s14
	s_mov_b32 s15, s24
	v_cvt_f32_u32_e32 v36, s24
	v_max_f32_e32 v36, 0.5, v36
	v_log_f32_e32 v36, v36
	s_cmp_lg_u32 s23, 2
	s_cbranch_scc1 .Lsqa_s2b
	v_mul_f32_e32 v35, 0.5, v35
.Lsqa_s2b:
	v_sub_f32_e32 v36, 0x41000b88, v36
	s_mov_b32 s23, 2
	s_add_i32 s22, s22, 1
.Lsqa_next:
	s_sub_u32 s26, s12, s13
	s_cmp_lt_u32 s26, 2
	s_cbranch_scc1 .Lsqa_collapse
	s_cmp_gt_i32 s13, -1
	s_cselect_b32 s26, -1, 0x80000000
	s_xor_b32 s16, s13, s26
	s_cmp_gt_i32 s12, -1
	s_cselect_b32 s26, -1, 0x80000000
	s_xor_b32 s17, s12, s26
	s_cmp_lt_i32 s22, 9
	s_cbranch_scc1 .Lsqa_interp
	s_bitcmp1_b32 s22, 0
	s_cbranch_scc0 .Lsqa_interp
	v_mov_b32_e32 v191, 0.5
	s_branch .Lsqa_frac
.Lsqa_interp:
	v_add_f32_e32 v191, v35, v36
	v_rcp_f32_e32 v191, v191
	s_nop 0
	v_mul_f32_e32 v191, v35, v191
.Lsqa_frac:
	v_mov_b32_e32 v0, s16
	v_sub_f32_e32 v34, s17, v0
	v_fma_f32 v191, v191, v34, v0
	v_ashrrev_i32_e32 v0, 31, v191
	v_bitop3_b32 v191, v0, v191, s38 bitop3:0x36
	s_nop 0
	v_readfirstlane_b32 s14, v191
	s_add_i32 s26, s13, 1
	s_max_u32 s14, s14, s26
	s_add_i32 s26, s12, -1
	s_min_u32 s14, s14, s26
	s_branch .Lsqa_count
.Lsqa_exact:
	s_mov_b32 s26, s14
	s_add_i32 s27, s14, -1
	s_mov_b32 s28, 0
	s_branch .Lsqa_fin
.Lsqa_collapse:
	s_mov_b32 s26, s13
	s_mov_b32 s27, s13
	s_sub_i32 s28, 0x100, s15
.Lsqa_fin:
	v_mov_b32_e32 v192, s26
	v_mov_b32_e32 v193, s27
	v_mov_b32_e32 v191, s28
.Lsqa_done:
.LBB0_173:
	s_or_b64 exec, exec, s[8:9]
	v_ashrrev_i32_e64 v88, 5, s75
	v_lshl_add_u32 v34, s20, 7, v88
	v_ashrrev_i32_e32 v35, 31, v34
	v_and_b32_e64 v0, s75, 30
	v_readlane_b32 s4, v255, 41
	v_lshlrev_b64 v[34:35], 7, v[34:35]
	v_ashrrev_i32_e32 v69, 31, v68
	v_lshlrev_b32_e32 v0, 2, v0
	v_readlane_b32 s5, v255, 42
	v_mov_b32_e32 v185, 0
	v_cmp_lt_i32_e32 vcc, 0, v191
	v_lshl_add_u64 v[34:35], v[34:35], 0, v[68:69]
	v_lshl_add_u64 v[36:37], s[4:5], 0, v[0:1]
	v_cmp_lt_i32_e64 s[4:5], 0, v190
	s_and_saveexec_b64 s[72:73], s[4:5]
	s_cbranch_execz .LBB0_179
	v_mov_b32_e32 v0, 0
	v_readfirstlane_b32 s14, v193
	v_cmp_gt_u32_e64 s[4:5], v176, s14
	v_cmp_gt_u32_e64 s[6:7], v175, s14
	v_cmp_gt_u32_e64 s[8:9], v174, s14
	v_cmp_gt_u32_e64 s[10:11], v173, s14
	v_addc_co_u32_e64 v0, s[12:13], v0, v0, s[4:5]
	v_addc_co_u32_e64 v0, s[12:13], v0, v0, s[6:7]
	v_addc_co_u32_e64 v0, s[12:13], v0, v0, s[8:9]
	v_addc_co_u32_e64 v0, s[12:13], v0, v0, s[10:11]
	v_mov_b32_e32 v185, 0
	v_cmp_gt_u32_e64 s[4:5], v170, s14
	v_cmp_gt_u32_e64 s[6:7], v168, s14
	v_cmp_gt_u32_e64 s[8:9], v169, s14
	v_cmp_gt_u32_e64 s[10:11], v167, s14
	v_addc_co_u32_e64 v0, s[12:13], v0, v0, s[4:5]
	v_addc_co_u32_e64 v0, s[12:13], v0, v0, s[6:7]
	v_addc_co_u32_e64 v0, s[12:13], v0, v0, s[8:9]
	v_addc_co_u32_e64 v0, s[12:13], v0, v0, s[10:11]
	v_cmp_gt_u32_e64 s[4:5], v161, s14
	v_cmp_gt_u32_e64 s[6:7], v159, s14
	v_cmp_gt_u32_e64 s[8:9], v160, s14
	v_cmp_gt_u32_e64 s[10:11], v158, s14
	v_addc_co_u32_e64 v0, s[12:13], v0, v0, s[4:5]
	v_addc_co_u32_e64 v0, s[12:13], v0, v0, s[6:7]
	v_addc_co_u32_e64 v0, s[12:13], v0, v0, s[8:9]
	v_addc_co_u32_e64 v0, s[12:13], v0, v0, s[10:11]
	v_cmp_gt_u32_e64 s[4:5], v157, s14
	v_cmp_gt_u32_e64 s[6:7], v155, s14
	v_cmp_gt_u32_e64 s[8:9], v156, s14
	v_cmp_gt_u32_e64 s[10:11], v153, s14
	v_addc_co_u32_e64 v0, s[12:13], v0, v0, s[4:5]
	v_addc_co_u32_e64 v0, s[12:13], v0, v0, s[6:7]
	v_addc_co_u32_e64 v0, s[12:13], v0, v0, s[8:9]
	v_addc_co_u32_e64 v0, s[12:13], v0, v0, s[10:11]
	v_cmp_gt_u32_e64 s[4:5], v154, s14
	v_cmp_gt_u32_e64 s[6:7], v151, s14
	v_cmp_gt_u32_e64 s[8:9], v152, s14
	v_cmp_gt_u32_e64 s[10:11], v150, s14
	v_addc_co_u32_e64 v0, s[12:13], v0, v0, s[4:5]
	v_addc_co_u32_e64 v0, s[12:13], v0, v0, s[6:7]
	v_addc_co_u32_e64 v0, s[12:13], v0, v0, s[8:9]
	v_addc_co_u32_e64 v0, s[12:13], v0, v0, s[10:11]
	v_cmp_gt_u32_e64 s[4:5], v149, s14
	v_cmp_gt_u32_e64 s[6:7], v145, s14
	v_cmp_gt_u32_e64 s[8:9], v148, s14
	v_cmp_gt_u32_e64 s[10:11], v144, s14
	v_addc_co_u32_e64 v0, s[12:13], v0, v0, s[4:5]
	v_addc_co_u32_e64 v0, s[12:13], v0, v0, s[6:7]
	v_addc_co_u32_e64 v0, s[12:13], v0, v0, s[8:9]
	v_addc_co_u32_e64 v0, s[12:13], v0, v0, s[10:11]
	v_cmp_gt_u32_e64 s[4:5], v147, s14
	v_cmp_gt_u32_e64 s[6:7], v143, s14
	v_cmp_gt_u32_e64 s[8:9], v146, s14
	v_cmp_gt_u32_e64 s[10:11], v142, s14
	v_addc_co_u32_e64 v0, s[12:13], v0, v0, s[4:5]
	v_addc_co_u32_e64 v0, s[12:13], v0, v0, s[6:7]
	v_addc_co_u32_e64 v0, s[12:13], v0, v0, s[8:9]
	v_addc_co_u32_e64 v0, s[12:13], v0, v0, s[10:11]
	v_cmp_gt_u32_e64 s[4:5], v141, s14
	v_cmp_gt_u32_e64 s[6:7], v139, s14
	v_cmp_gt_u32_e64 s[8:9], v140, s14
	v_cmp_gt_u32_e64 s[10:11], v138, s14
	v_addc_co_u32_e64 v0, s[12:13], v0, v0, s[4:5]
	v_addc_co_u32_e64 v0, s[12:13], v0, v0, s[6:7]
	v_addc_co_u32_e64 v0, s[12:13], v0, v0, s[8:9]
	v_addc_co_u32_e64 v0, s[12:13], v0, v0, s[10:11]
	s_and_saveexec_b64 s[90:91], vcc
	s_cbranch_execz .LBB0_176
; __device__ __forceinline__ void select_query(const unsigned (&u)[64], unsigned vmax, int q, int b, int lane, unsigned* MASKb) {
;     ...
;             if (rrem > 0) {
;                 int ec = 0;
; #pragma unroll
;                 for (int e = 0; e < 32; ++e) ec += (u[B * 32 + e] == T) ? 1 : 0;
;                 int incl = ec;
; #pragma unroll
;                 for (int o = 1; o < 64; o <<= 1) { const int t = __shfl_up(incl, o); if (lane >= o) incl += t; }
;                 const int total = __builtin_amdgcn_readlane(incl, 63);
;                 const int quota = rrem - tbase - (incl - ec);
;                 int taken = 0;
; #pragma unroll
;                 for (int e = 0; e < 32; ++e) { const bool is = (u[B * 32 + e] == T) && (taken < quota); w |= is ? (1u << e) : 0u; taken += is ? 1 : 0; }
	v_cmp_eq_u32_e64 s[4:5], v176, v192
	v_cmp_eq_u32_e64 s[6:7], v174, v192
	v_cmp_eq_u32_e64 s[8:9], v175, v192
	v_cndmask_b32_e64 v174, 0, 1, s[4:5]
	v_cmp_eq_u32_e64 s[10:11], v170, v192
	v_addc_co_u32_e64 v174, s[12:13], 0, v174, s[8:9]
	v_cndmask_b32_e64 v170, 0, 1, s[6:7]
	v_cmp_eq_u32_e64 s[12:13], v173, v192
	v_cmp_eq_u32_e64 s[14:15], v169, v192
	v_cndmask_b32_e64 v169, 0, 1, s[10:11]
	v_addc_co_u32_e64 v170, s[18:19], v174, v170, s[12:13]
	v_cmp_eq_u32_e64 s[18:19], v168, v192
	v_cmp_eq_u32_e64 s[16:17], v161, v192
	v_cndmask_b32_e64 v161, 0, 1, s[14:15]
	v_addc_co_u32_e64 v168, s[24:25], v170, v169, s[18:19]
	v_cmp_eq_u32_e64 s[24:25], v167, v192
	v_cmp_eq_u32_e64 s[20:21], v160, v192
	v_cndmask_b32_e64 v160, 0, 1, s[16:17]
	v_addc_co_u32_e64 v161, s[28:29], v168, v161, s[24:25]
	v_cmp_eq_u32_e64 s[28:29], v159, v192
	v_cmp_eq_u32_e64 s[22:23], v157, v192
	v_cndmask_b32_e64 v157, 0, 1, s[20:21]
	v_addc_co_u32_e64 v159, s[36:37], v161, v160, s[28:29]
	v_cmp_eq_u32_e64 s[36:37], v158, v192
	v_cmp_eq_u32_e64 s[26:27], v156, v192
	v_cndmask_b32_e64 v156, 0, 1, s[22:23]
	v_addc_co_u32_e64 v157, s[42:43], v159, v157, s[36:37]
	v_cmp_eq_u32_e64 s[42:43], v155, v192
	v_cmp_eq_u32_e64 s[30:31], v154, v192
	v_cndmask_b32_e64 v154, 0, 1, s[26:27]
	v_addc_co_u32_e64 v155, s[48:49], v157, v156, s[42:43]
	v_cmp_eq_u32_e64 s[48:49], v153, v192
	v_cmp_eq_u32_e64 s[34:35], v152, v192
	v_cndmask_b32_e64 v152, 0, 1, s[30:31]
	v_addc_co_u32_e64 v153, s[52:53], v155, v154, s[48:49]
	v_cmp_eq_u32_e64 s[52:53], v151, v192
	s_mov_b32 s82, s38
	v_cmp_eq_u32_e64 s[38:39], v149, v192
	v_addc_co_u32_e64 v151, s[56:57], v153, v152, s[52:53]
	v_cndmask_b32_e64 v149, 0, 1, s[34:35]
	v_cmp_eq_u32_e64 s[56:57], v150, v192
	v_cmp_eq_u32_e64 s[40:41], v148, v192
	v_cndmask_b32_e64 v148, 0, 1, s[38:39]
	v_addc_co_u32_e64 v149, s[58:59], v151, v149, s[56:57]
	v_cmp_eq_u32_e64 s[58:59], v145, v192
	v_cmp_eq_u32_e64 s[44:45], v147, v192
	v_cndmask_b32_e64 v147, 0, 1, s[40:41]
	v_addc_co_u32_e64 v145, s[60:61], v149, v148, s[58:59]
	v_cmp_eq_u32_e64 s[60:61], v144, v192
	v_cmp_eq_u32_e64 s[46:47], v146, v192
	v_cndmask_b32_e64 v146, 0, 1, s[44:45]
	v_addc_co_u32_e64 v144, s[62:63], v145, v147, s[60:61]
	v_cmp_eq_u32_e64 s[62:63], v143, v192
	v_cmp_eq_u32_e64 s[50:51], v141, v192
	v_cndmask_b32_e64 v141, 0, 1, s[46:47]
	v_addc_co_u32_e64 v143, s[64:65], v144, v146, s[62:63]
	v_cmp_eq_u32_e64 s[64:65], v142, v192
	v_cmp_eq_u32_e64 s[54:55], v140, v192
	v_cndmask_b32_e64 v140, 0, 1, s[50:51]
	v_addc_co_u32_e64 v141, s[66:67], v143, v141, s[64:65]
	v_cmp_eq_u32_e64 s[66:67], v139, v192
	v_cndmask_b32_e64 v69, 0, 1, s[54:55]
	s_nop 0
	v_addc_co_u32_e64 v139, s[68:69], v141, v140, s[66:67]
	v_cmp_eq_u32_e64 s[68:69], v138, v192
	s_nop 1
	v_addc_co_u32_e64 v69, s[70:71], v139, v69, s[68:69]
	ds_bpermute_b32 v138, v100, v69
	v_cmp_lt_i32_e64 s[70:71], 0, v68
	s_waitcnt lgkmcnt(0)
	s_nop 0
	v_cndmask_b32_e64 v138, 0, v138, s[70:71]
	v_add_u32_e32 v138, v138, v69
	ds_bpermute_b32 v139, v101, v138
	v_cmp_lt_i32_e64 s[70:71], 1, v68
	v_add_u32_e32 v69, v69, v191
	s_waitcnt lgkmcnt(0)
	v_cndmask_b32_e64 v139, 0, v139, s[70:71]
	v_add_u32_e32 v138, v139, v138
	ds_bpermute_b32 v139, v102, v138
	v_cmp_lt_i32_e64 s[70:71], 3, v68
	s_waitcnt lgkmcnt(0)
	s_nop 0
	v_cndmask_b32_e64 v139, 0, v139, s[70:71]
	v_add_u32_e32 v138, v139, v138
	ds_bpermute_b32 v139, v103, v138
	v_cmp_lt_i32_e64 s[70:71], 7, v68
	s_waitcnt lgkmcnt(0)
	s_nop 0
	v_cndmask_b32_e64 v139, 0, v139, s[70:71]
	v_add_u32_e32 v138, v139, v138
	ds_bpermute_b32 v139, v104, v138
	v_cmp_lt_i32_e64 s[70:71], 15, v68
	s_waitcnt lgkmcnt(0)
	s_nop 0
	v_cndmask_b32_e64 v139, 0, v139, s[70:71]
	v_add_u32_e32 v138, v139, v138
	ds_bpermute_b32 v139, v105, v138
	v_cmp_lt_i32_e64 s[70:71], 31, v68
	s_waitcnt lgkmcnt(0)
	s_nop 0
	v_cndmask_b32_e64 v139, 0, v139, s[70:71]
	v_add_u32_e32 v138, v139, v138
	v_sub_u32_e32 v69, v69, v138
	v_cmp_lt_i32_e64 s[70:71], 0, v69
	s_and_b64 s[68:69], s[68:69], s[70:71]
	v_cndmask_b32_e64 v139, 0, 1, s[68:69]
	v_cmp_gt_i32_e64 s[68:69], v69, v139
	s_and_b64 s[54:55], s[54:55], s[68:69]
	v_cndmask_b32_e64 v140, 0, 2, s[54:55]
	v_cndmask_b32_e64 v141, 0, 1, s[54:55]
	v_addc_co_u32_e64 v142, s[54:55], 0, v139, s[54:55]
	v_cmp_lt_i32_e64 s[54:55], v142, v69
	s_and_b64 s[54:55], s[66:67], s[54:55]
	s_nop 0
	v_cndmask_b32_e64 v142, 0, 4, s[54:55]
	v_addc_co_u32_e64 v141, s[54:55], v141, v139, s[54:55]
	v_cmp_lt_i32_e64 s[54:55], v141, v69
	s_and_b64 s[50:51], s[50:51], s[54:55]
	v_cndmask_b32_e64 v143, 0, 8, s[50:51]
	v_cndmask_b32_e64 v144, 0, 1, s[50:51]
	v_addc_co_u32_e64 v145, s[50:51], 0, v141, s[50:51]
	v_cmp_lt_i32_e64 s[50:51], v145, v69
	s_and_b64 s[50:51], s[64:65], s[50:51]
	v_or3_b32 v140, v140, v142, v143
	v_cndmask_b32_e64 v146, 0, 16, s[50:51]
	v_cndmask_b32_e64 v147, 0, 1, s[50:51]
	v_addc_co_u32_e64 v141, s[50:51], v141, v144, s[50:51]
	v_cmp_lt_i32_e64 s[50:51], v141, v69
	s_and_b64 s[46:47], s[46:47], s[50:51]
	v_cndmask_b32_e64 v144, 0, 32, s[46:47]
	v_cndmask_b32_e64 v148, 0, 1, s[46:47]
	v_addc_co_u32_e64 v145, s[46:47], v145, v147, s[46:47]
	v_cmp_lt_i32_e64 s[46:47], v145, v69
	s_and_b64 s[46:47], s[62:63], s[46:47]
	v_or3_b32 v140, v140, v146, v144
	v_cndmask_b32_e64 v147, 0, 64, s[46:47]
	v_cndmask_b32_e64 v149, 0, 1, s[46:47]
	v_addc_co_u32_e64 v141, s[46:47], v141, v148, s[46:47]
	v_cmp_lt_i32_e64 s[46:47], v141, v69
	s_and_b64 s[44:45], s[44:45], s[46:47]
	v_mov_b32_e32 v148, 0x80
	v_cndmask_b32_e64 v148, 0, v148, s[44:45]
	v_cndmask_b32_e64 v150, 0, 1, s[44:45]
	v_addc_co_u32_e64 v145, s[44:45], v145, v149, s[44:45]
	v_cmp_lt_i32_e64 s[44:45], v145, v69
	s_and_b64 s[44:45], s[60:61], s[44:45]
; __device__ __forceinline__ void select_query(const unsigned (&u)[64], unsigned vmax, int q, int b, int lane, unsigned* MASKb) {
;     ...
;                 const int total = __builtin_amdgcn_readlane(incl, 63);
;                 const int quota = rrem - tbase - (incl - ec);
;                 int taken = 0;
; #pragma unroll
;                 for (int e = 0; e < 32; ++e) { const bool is = (u[B * 32 + e] == T) && (taken < quota); w |= is ? (1u << e) : 0u; taken += is ? 1 : 0; }
;                 tbase += total;
;             }
;             if (64 * B + lane <= (q >> 5)) __hip_atomic_store(MASKb + ((size_t)(b * 128 + (q >> 5)) * 128 + 64 * B + lane) * 32 + (q & 31), w, __ATOMIC_RELAXED, __HIP_MEMORY_SCOPE_AGENT);
	v_mov_b32_e32 v149, 0x100
	v_cndmask_b32_e64 v149, 0, v149, s[44:45]
	v_cndmask_b32_e64 v151, 0, 1, s[44:45]
	v_addc_co_u32_e64 v141, s[44:45], v141, v150, s[44:45]
	v_cmp_lt_i32_e64 s[44:45], v141, v69
	s_and_b64 s[40:41], s[40:41], s[44:45]
	v_mov_b32_e32 v150, 0x200
	v_cndmask_b32_e64 v150, 0, v150, s[40:41]
	v_cndmask_b32_e64 v152, 0, 1, s[40:41]
	v_addc_co_u32_e64 v145, s[40:41], v145, v151, s[40:41]
	v_cmp_lt_i32_e64 s[40:41], v145, v69
	s_and_b64 s[40:41], s[58:59], s[40:41]
	v_mov_b32_e32 v151, 0x400
	v_cndmask_b32_e64 v151, 0, v151, s[40:41]
	v_cndmask_b32_e64 v153, 0, 1, s[40:41]
	v_addc_co_u32_e64 v141, s[40:41], v141, v152, s[40:41]
	v_cmp_lt_i32_e64 s[40:41], v141, v69
	s_and_b64 s[38:39], s[38:39], s[40:41]
	v_mov_b32_e32 v152, 0x800
	v_cndmask_b32_e64 v152, 0, v152, s[38:39]
	v_cndmask_b32_e64 v154, 0, 1, s[38:39]
	v_addc_co_u32_e64 v145, s[38:39], v145, v153, s[38:39]
	v_cmp_lt_i32_e64 s[38:39], v145, v69
	s_and_b64 s[38:39], s[56:57], s[38:39]
	v_mov_b32_e32 v153, 0x1000
	v_cndmask_b32_e64 v153, 0, v153, s[38:39]
	v_cndmask_b32_e64 v155, 0, 1, s[38:39]
	v_addc_co_u32_e64 v141, s[38:39], v141, v154, s[38:39]
	v_cmp_lt_i32_e64 s[38:39], v141, v69
	s_and_b64 s[34:35], s[34:35], s[38:39]
	v_cndmask_b32_e64 v154, 0, v240, s[34:35]
	v_cndmask_b32_e64 v156, 0, 1, s[34:35]
	v_addc_co_u32_e64 v145, s[34:35], v145, v155, s[34:35]
	v_cmp_lt_i32_e64 s[34:35], v145, v69
	s_and_b64 s[34:35], s[52:53], s[34:35]
	v_mov_b32_e32 v155, 0x4000
	v_cndmask_b32_e64 v155, 0, v155, s[34:35]
	v_cndmask_b32_e64 v157, 0, 1, s[34:35]
	v_addc_co_u32_e64 v141, s[34:35], v141, v156, s[34:35]
	v_cmp_lt_i32_e64 s[34:35], v141, v69
	s_and_b64 s[30:31], s[30:31], s[34:35]
	v_mov_b32_e32 v156, 0x8000
	v_cndmask_b32_e64 v156, 0, v156, s[30:31]
	v_cndmask_b32_e64 v158, 0, 1, s[30:31]
	v_addc_co_u32_e64 v145, s[30:31], v145, v157, s[30:31]
	v_cmp_lt_i32_e64 s[30:31], v145, v69
	s_and_b64 s[30:31], s[48:49], s[30:31]
	v_mov_b32_e32 v157, 0x10000
	v_cndmask_b32_e64 v157, 0, v157, s[30:31]
	v_cndmask_b32_e64 v159, 0, 1, s[30:31]
	v_addc_co_u32_e64 v141, s[30:31], v141, v158, s[30:31]
	v_cmp_lt_i32_e64 s[30:31], v141, v69
	s_and_b64 s[26:27], s[26:27], s[30:31]
	v_mov_b32_e32 v158, 0x20000
	v_cndmask_b32_e64 v158, 0, v158, s[26:27]
	v_cndmask_b32_e64 v160, 0, 1, s[26:27]
	v_addc_co_u32_e64 v145, s[26:27], v145, v159, s[26:27]
	v_cmp_lt_i32_e64 s[26:27], v145, v69
	s_and_b64 s[26:27], s[42:43], s[26:27]
	v_mov_b32_e32 v159, 0x40000
	v_cndmask_b32_e64 v159, 0, v159, s[26:27]
	v_cndmask_b32_e64 v161, 0, 1, s[26:27]
	v_addc_co_u32_e64 v141, s[26:27], v141, v160, s[26:27]
	v_cmp_lt_i32_e64 s[26:27], v141, v69
	s_and_b64 s[22:23], s[22:23], s[26:27]
	v_mov_b32_e32 v160, 0x80000
	v_cndmask_b32_e64 v160, 0, v160, s[22:23]
	v_cndmask_b32_e64 v167, 0, 1, s[22:23]
	v_addc_co_u32_e64 v145, s[22:23], v145, v161, s[22:23]
	v_cmp_lt_i32_e64 s[22:23], v145, v69
	s_and_b64 s[22:23], s[36:37], s[22:23]
	v_mov_b32_e32 v161, 0x100000
	v_cndmask_b32_e64 v161, 0, v161, s[22:23]
	v_cndmask_b32_e64 v168, 0, 1, s[22:23]
	v_addc_co_u32_e64 v141, s[22:23], v141, v167, s[22:23]
	v_cmp_lt_i32_e64 s[22:23], v141, v69
	s_and_b64 s[20:21], s[20:21], s[22:23]
	v_mov_b32_e32 v167, 0x200000
	v_cndmask_b32_e64 v167, 0, v167, s[20:21]
	v_cndmask_b32_e64 v169, 0, 1, s[20:21]
	v_addc_co_u32_e64 v145, s[20:21], v145, v168, s[20:21]
	v_cmp_lt_i32_e64 s[20:21], v145, v69
	s_and_b64 s[20:21], s[28:29], s[20:21]
	v_mov_b32_e32 v168, 0x400000
	v_cndmask_b32_e64 v168, 0, v168, s[20:21]
	v_cndmask_b32_e64 v170, 0, 1, s[20:21]
	v_addc_co_u32_e64 v141, s[20:21], v141, v169, s[20:21]
	v_cmp_lt_i32_e64 s[20:21], v141, v69
	s_and_b64 s[16:17], s[16:17], s[20:21]
	v_mov_b32_e32 v169, 0x800000
	v_cndmask_b32_e64 v169, 0, v169, s[16:17]
	v_cndmask_b32_e64 v173, 0, 1, s[16:17]
	v_addc_co_u32_e64 v145, s[16:17], v145, v170, s[16:17]
	v_cmp_lt_i32_e64 s[16:17], v145, v69
	s_and_b64 s[16:17], s[24:25], s[16:17]
	v_mov_b32_e32 v170, 0x1000000
	v_cndmask_b32_e64 v170, 0, v170, s[16:17]
	v_cndmask_b32_e64 v174, 0, 1, s[16:17]
	v_addc_co_u32_e64 v141, s[16:17], v141, v173, s[16:17]
	v_cmp_lt_i32_e64 s[16:17], v141, v69
	s_and_b64 s[14:15], s[14:15], s[16:17]
	v_bfrev_b32_e32 v173, 64
	v_cndmask_b32_e64 v173, 0, v173, s[14:15]
	v_cndmask_b32_e64 v175, 0, 1, s[14:15]
	v_addc_co_u32_e64 v145, s[14:15], v145, v174, s[14:15]
	v_cmp_lt_i32_e64 s[14:15], v145, v69
	s_and_b64 s[14:15], s[18:19], s[14:15]
	v_bfrev_b32_e32 v174, 32
	v_cndmask_b32_e64 v174, 0, v174, s[14:15]
	v_cndmask_b32_e64 v176, 0, 1, s[14:15]
	v_addc_co_u32_e64 v141, s[14:15], v141, v175, s[14:15]
	v_cmp_lt_i32_e64 s[14:15], v141, v69
	s_and_b64 s[10:11], s[10:11], s[14:15]
	v_bfrev_b32_e32 v175, 16
	v_cndmask_b32_e64 v175, 0, v175, s[10:11]
	v_cndmask_b32_e64 v185, 0, 1, s[10:11]
	v_addc_co_u32_e64 v145, s[10:11], v145, v176, s[10:11]
	v_cmp_lt_i32_e64 s[10:11], v145, v69
	v_or3_b32 v140, v140, v147, v148
	s_and_b64 s[10:11], s[12:13], s[10:11]
	v_bfrev_b32_e32 v176, 8
	v_or3_b32 v140, v140, v149, v150
	v_cndmask_b32_e64 v176, 0, v176, s[10:11]
	v_cndmask_b32_e64 v194, 0, 1, s[10:11]
	v_addc_co_u32_e64 v141, s[10:11], v141, v185, s[10:11]
	v_or3_b32 v140, v140, v151, v152
	v_cmp_lt_i32_e64 s[10:11], v141, v69
	v_or3_b32 v140, v140, v153, v154
	s_and_b64 s[6:7], s[6:7], s[10:11]
	v_bfrev_b32_e32 v185, 4
	v_or3_b32 v140, v140, v155, v156
	v_cndmask_b32_e64 v185, 0, v185, s[6:7]
	v_cndmask_b32_e64 v195, 0, 1, s[6:7]
	v_addc_co_u32_e64 v145, s[6:7], v145, v194, s[6:7]
	v_or3_b32 v140, v140, v157, v158
	v_cmp_lt_i32_e64 s[6:7], v145, v69
	v_or3_b32 v140, v140, v159, v160
	s_and_b64 s[6:7], s[8:9], s[6:7]
	v_or3_b32 v140, v140, v161, v167
	v_cndmask_b32_e64 v145, 0, 2.0, s[6:7]
	v_addc_co_u32_e64 v141, s[6:7], v141, v195, s[6:7]
	v_or3_b32 v140, v140, v168, v169
	v_cmp_lt_i32_e64 s[6:7], v141, v69
	v_or3_b32 v140, v140, v170, v173
	s_and_b64 s[4:5], s[4:5], s[6:7]
	v_bfrev_b32_e32 v69, 1
	v_or3_b32 v140, v140, v174, v175
	v_cndmask_b32_e64 v69, 0, v69, s[4:5]
	v_or3_b32 v140, v140, v176, v185
	v_or3_b32 v69, v140, v145, v69
	v_readlane_b32 s4, v138, 63
	s_mov_b32 s38, s82
	v_or3_b32 v0, v69, v139, v0
	v_mov_b32_e32 v185, s4

; __device__ __forceinline__ int count_ge(const unsigned (&u)[64], unsigned cand, int nblk) {
;     int c0 = 0, c1 = 0;
;     const unsigned ts = __builtin_amdgcn_readfirstlane(cand);
; #pragma unroll
;     for (int B = 0; B < 2; ++B) {
;         if (B < nblk) {
; #pragma unroll
;             for (int i = 0; i < 32; i += 4) CNT4(c0, c1, ts, u[B * 32 + i], u[B * 32 + i + 1], u[B * 32 + i + 2], u[B * 32 + i + 3]);
;         }
;     }
;     return wave_isum(c0 + c1);
; __device__ __forceinline__ void select_query(const unsigned (&u)[64], unsigned vmax, int q, int b, int lane, unsigned* MASKb) {
;     ...
;     if (n > 256) {
;         const unsigned kmax = wave_umax(vmax);
;         const unsigned K0 = 0x80000000u;
;         bool exact = false, done = false;
;         unsigned lo = 0u, hi = 0u; float Llo = 1.f, Lhi = 1.f;
;         const float L256 = 8.0028150156f;
;         const int cpos = count_ge(u, K0 + 1u, nblk);
;         if (cpos == 256) { T = K0 + 1u; exact = true; done = true; }
;         else if (cpos > 256) { lo = K0 + 1u; Llo = __log2f((float)cpos) - L256; hi = kmax + 1u; Lhi = L256 + 1.f; }
.LBB0_184:
	s_or_b64 exec, exec, s[70:71]
	v_add_u32_e32 v0, 0x801, v106
	v_ashrrev_i32_e32 v0, 11, v0
	s_mov_b64 s[8:9], exec
	v_mov_b32_e32 v76, 0
	v_mov_b32_e32 v77, 0
	v_mov_b32_e32 v69, 0
	s_cmpk_gt_i32 s75, 0xfe
	s_cbranch_scc0 .Lsqb_done
	s_add_i32 s25, s75, 0x801
	s_lshr_b32 s25, s25, 11
	v_max_u32_dpp v142, v177, v177 row_shr:1 row_mask:0xf bank_mask:0xf bound_ctrl:1
	s_nop 1
	v_max_u32_dpp v142, v142, v142 row_shr:2 row_mask:0xf bank_mask:0xf bound_ctrl:1
	s_nop 1
	v_max_u32_dpp v142, v142, v142 row_shr:4 row_mask:0xf bank_mask:0xf bound_ctrl:1
	s_nop 1
	v_max_u32_dpp v142, v142, v142 row_shr:8 row_mask:0xf bank_mask:0xf bound_ctrl:1
	s_nop 1
	v_max_u32_dpp v142, v142, v142 row_bcast:15 row_mask:0xa bank_mask:0xf
	s_nop 1
	v_max_u32_dpp v142, v142, v142 row_bcast:31 row_mask:0xc bank_mask:0xf
	s_nop 0
	v_readlane_b32 s19, v142, 63
	s_mov_b32 s21, 0
	s_mov_b32 s14, 0x80000001
.Lsqb_count:
	v_mov_b32_e32 v138, 0
	v_mov_b32_e32 v140, 0
	v_cmp_le_u32_e64 s[4:5], s14, v98
	v_cmp_le_u32_e64 s[6:7], s14, v107
	v_cmp_le_u32_e64 s[10:11], s14, v99
	v_cmp_le_u32_e64 s[26:27], s14, v108
	v_addc_co_u32_e64 v138, s[28:29], 0, v138, s[4:5]
	v_addc_co_u32_e64 v140, s[30:31], 0, v140, s[6:7]
	v_addc_co_u32_e64 v138, s[28:29], 0, v138, s[10:11]
	v_addc_co_u32_e64 v140, s[30:31], 0, v140, s[26:27]
	v_cmp_le_u32_e64 s[4:5], s14, v109
	v_cmp_le_u32_e64 s[6:7], s14, v113
	v_cmp_le_u32_e64 s[10:11], s14, v110
	v_cmp_le_u32_e64 s[26:27], s14, v114
	v_addc_co_u32_e64 v138, s[28:29], 0, v138, s[4:5]
	v_addc_co_u32_e64 v140, s[30:31], 0, v140, s[6:7]
	v_addc_co_u32_e64 v138, s[28:29], 0, v138, s[10:11]
	v_addc_co_u32_e64 v140, s[30:31], 0, v140, s[26:27]
	v_cmp_le_u32_e64 s[4:5], s14, v111
	v_cmp_le_u32_e64 s[6:7], s14, v115
	v_cmp_le_u32_e64 s[10:11], s14, v112
	v_cmp_le_u32_e64 s[26:27], s14, v116
	v_addc_co_u32_e64 v138, s[28:29], 0, v138, s[4:5]
	v_addc_co_u32_e64 v140, s[30:31], 0, v140, s[6:7]
	v_addc_co_u32_e64 v138, s[28:29], 0, v138, s[10:11]
	v_addc_co_u32_e64 v140, s[30:31], 0, v140, s[26:27]
	v_cmp_le_u32_e64 s[4:5], s14, v117
	v_cmp_le_u32_e64 s[6:7], s14, v119
	v_cmp_le_u32_e64 s[10:11], s14, v118
	v_cmp_le_u32_e64 s[26:27], s14, v121
	v_addc_co_u32_e64 v138, s[28:29], 0, v138, s[4:5]
	v_addc_co_u32_e64 v140, s[30:31], 0, v140, s[6:7]
	v_addc_co_u32_e64 v138, s[28:29], 0, v138, s[10:11]
	v_addc_co_u32_e64 v140, s[30:31], 0, v140, s[26:27]
	v_cmp_le_u32_e64 s[4:5], s14, v120
	v_cmp_le_u32_e64 s[6:7], s14, v123
	v_cmp_le_u32_e64 s[10:11], s14, v122
	v_cmp_le_u32_e64 s[26:27], s14, v124
	v_addc_co_u32_e64 v138, s[28:29], 0, v138, s[4:5]
	v_addc_co_u32_e64 v140, s[30:31], 0, v140, s[6:7]
	v_addc_co_u32_e64 v138, s[28:29], 0, v138, s[10:11]
	v_addc_co_u32_e64 v140, s[30:31], 0, v140, s[26:27]
	v_cmp_le_u32_e64 s[4:5], s14, v125
	v_cmp_le_u32_e64 s[6:7], s14, v127
	v_cmp_le_u32_e64 s[10:11], s14, v126
	v_cmp_le_u32_e64 s[26:27], s14, v128
	v_addc_co_u32_e64 v138, s[28:29], 0, v138, s[4:5]
	v_addc_co_u32_e64 v140, s[30:31], 0, v140, s[6:7]
	v_addc_co_u32_e64 v138, s[28:29], 0, v138, s[10:11]
	v_addc_co_u32_e64 v140, s[30:31], 0, v140, s[26:27]
	v_cmp_le_u32_e64 s[4:5], s14, v129
	v_cmp_le_u32_e64 s[6:7], s14, v131
	v_cmp_le_u32_e64 s[10:11], s14, v130
	v_cmp_le_u32_e64 s[26:27], s14, v132
	v_addc_co_u32_e64 v138, s[28:29], 0, v138, s[4:5]
	v_addc_co_u32_e64 v140, s[30:31], 0, v140, s[6:7]
	v_addc_co_u32_e64 v138, s[28:29], 0, v138, s[10:11]
	v_addc_co_u32_e64 v140, s[30:31], 0, v140, s[26:27]
	v_cmp_le_u32_e64 s[4:5], s14, v133
	v_cmp_le_u32_e64 s[6:7], s14, v134
	v_cmp_le_u32_e64 s[10:11], s14, v136
	v_cmp_le_u32_e64 s[26:27], s14, v137
	v_addc_co_u32_e64 v138, s[28:29], 0, v138, s[4:5]
	v_addc_co_u32_e64 v140, s[30:31], 0, v140, s[6:7]
	v_addc_co_u32_e64 v138, s[28:29], 0, v138, s[10:11]
	v_addc_co_u32_e64 v140, s[30:31], 0, v140, s[26:27]
	s_cmp_lt_u32 s25, 2
	s_cbranch_scc1 .Lsqb_red
	v_cmp_le_u32_e64 s[4:5], s14, v46
	v_cmp_le_u32_e64 s[6:7], s14, v48
	v_cmp_le_u32_e64 s[10:11], s14, v47
	v_cmp_le_u32_e64 s[26:27], s14, v49
	v_addc_co_u32_e64 v138, s[28:29], 0, v138, s[4:5]
	v_addc_co_u32_e64 v140, s[30:31], 0, v140, s[6:7]
	v_addc_co_u32_e64 v138, s[28:29], 0, v138, s[10:11]
	v_addc_co_u32_e64 v140, s[30:31], 0, v140, s[26:27]
	v_cmp_le_u32_e64 s[4:5], s14, v42
	v_cmp_le_u32_e64 s[6:7], s14, v50
	v_cmp_le_u32_e64 s[10:11], s14, v43
	v_cmp_le_u32_e64 s[26:27], s14, v44
	v_addc_co_u32_e64 v138, s[28:29], 0, v138, s[4:5]
	v_addc_co_u32_e64 v140, s[30:31], 0, v140, s[6:7]
	v_addc_co_u32_e64 v138, s[28:29], 0, v138, s[10:11]
	v_addc_co_u32_e64 v140, s[30:31], 0, v140, s[26:27]
	v_cmp_le_u32_e64 s[4:5], s14, v38
	v_cmp_le_u32_e64 s[6:7], s14, v45
	v_cmp_le_u32_e64 s[10:11], s14, v39
	v_cmp_le_u32_e64 s[26:27], s14, v40
	v_addc_co_u32_e64 v138, s[28:29], 0, v138, s[4:5]
	v_addc_co_u32_e64 v140, s[30:31], 0, v140, s[6:7]
	v_addc_co_u32_e64 v138, s[28:29], 0, v138, s[10:11]
	v_addc_co_u32_e64 v140, s[30:31], 0, v140, s[26:27]
	v_cmp_le_u32_e64 s[4:5], s14, v41
	v_cmp_le_u32_e64 s[6:7], s14, v52
	v_cmp_le_u32_e64 s[10:11], s14, v51
	v_cmp_le_u32_e64 s[26:27], s14, v54
	v_addc_co_u32_e64 v138, s[28:29], 0, v138, s[4:5]
	v_addc_co_u32_e64 v140, s[30:31], 0, v140, s[6:7]
	v_addc_co_u32_e64 v138, s[28:29], 0, v138, s[10:11]
	v_addc_co_u32_e64 v140, s[30:31], 0, v140, s[26:27]
	v_cmp_le_u32_e64 s[4:5], s14, v53
	v_cmp_le_u32_e64 s[6:7], s14, v56
	v_cmp_le_u32_e64 s[10:11], s14, v55
	v_cmp_le_u32_e64 s[26:27], s14, v57
	v_addc_co_u32_e64 v138, s[28:29], 0, v138, s[4:5]
	v_addc_co_u32_e64 v140, s[30:31], 0, v140, s[6:7]
	v_addc_co_u32_e64 v138, s[28:29], 0, v138, s[10:11]
	v_addc_co_u32_e64 v140, s[30:31], 0, v140, s[26:27]
	v_cmp_le_u32_e64 s[4:5], s14, v58
	v_cmp_le_u32_e64 s[6:7], s14, v60
	v_cmp_le_u32_e64 s[10:11], s14, v59
	v_cmp_le_u32_e64 s[26:27], s14, v61
	v_addc_co_u32_e64 v138, s[28:29], 0, v138, s[4:5]
	v_addc_co_u32_e64 v140, s[30:31], 0, v140, s[6:7]
	v_addc_co_u32_e64 v138, s[28:29], 0, v138, s[10:11]
	v_addc_co_u32_e64 v140, s[30:31], 0, v140, s[26:27]
	v_cmp_le_u32_e64 s[4:5], s14, v62
	v_cmp_le_u32_e64 s[6:7], s14, v64
	v_cmp_le_u32_e64 s[10:11], s14, v63
	v_cmp_le_u32_e64 s[26:27], s14, v65
	v_addc_co_u32_e64 v138, s[28:29], 0, v138, s[4:5]
	v_addc_co_u32_e64 v140, s[30:31], 0, v140, s[6:7]
	v_addc_co_u32_e64 v138, s[28:29], 0, v138, s[10:11]
	v_addc_co_u32_e64 v140, s[30:31], 0, v140, s[26:27]
	v_cmp_le_u32_e64 s[4:5], s14, v72
	v_cmp_le_u32_e64 s[6:7], s14, v73
	v_cmp_le_u32_e64 s[10:11], s14, v74
	v_cmp_le_u32_e64 s[26:27], s14, v75
	v_addc_co_u32_e64 v138, s[28:29], 0, v138, s[4:5]
	v_addc_co_u32_e64 v140, s[30:31], 0, v140, s[6:7]
	v_addc_co_u32_e64 v138, s[28:29], 0, v138, s[10:11]
	v_addc_co_u32_e64 v140, s[30:31], 0, v140, s[26:27]
; __device__ __forceinline__ void select_query(const unsigned (&u)[64], unsigned vmax, int q, int b, int lane, unsigned* MASKb) {
;     ...
;         const float L256 = 8.0028150156f;
;         const int cpos = count_ge(u, K0 + 1u, nblk);
;         if (cpos == 256) { T = K0 + 1u; exact = true; done = true; }
;         else if (cpos > 256) { lo = K0 + 1u; Llo = __log2f((float)cpos) - L256; hi = kmax + 1u; Lhi = L256 + 1.f; }
;         else {
;             const int c0 = count_ge(u, K0, nblk);
;             if (c0 >= 256) { T = K0; exact = (c0 == 256); done = true; }
;             else {
;                 unsigned vmin = 0xffffffffu;
; #pragma unroll
;                 for (int i = 0; i < 64; ++i) vmin = min(vmin, u[i] - 1u);
;                 lo = ~wave_umax(~vmin) + 1u; Llo = __log2f((float)n) - L256; hi = K0; Lhi = L256 - __log2f(fmaxf((float)c0, 0.5f));
;             }
;         }
.Lsqb_red:
	v_add_u32_e32 v138, v138, v140
	s_nop 1
	v_add_u32_dpp v138, v138, v138 row_shr:1 row_mask:0xf bank_mask:0xf bound_ctrl:1
	s_nop 1
	v_add_u32_dpp v138, v138, v138 row_shr:2 row_mask:0xf bank_mask:0xf bound_ctrl:1
	s_nop 1
	v_add_u32_dpp v138, v138, v138 row_shr:4 row_mask:0xf bank_mask:0xf bound_ctrl:1
	s_nop 1
	v_add_u32_dpp v138, v138, v138 row_shr:8 row_mask:0xf bank_mask:0xf bound_ctrl:1
	s_nop 1
	v_add_u32_dpp v138, v138, v138 row_bcast:15 row_mask:0xa bank_mask:0xf
	s_nop 1
	v_add_u32_dpp v138, v138, v138 row_bcast:31 row_mask:0xc bank_mask:0xf
	s_nop 0
	v_readlane_b32 s24, v138, 63
	s_cmp_eq_u32 s21, 2
	s_cbranch_scc1 .Lsqb_st2
	s_cmp_eq_u32 s21, 1
	s_cbranch_scc1 .Lsqb_st1
	s_cmpk_eq_i32 s24, 0x100
	s_cbranch_scc1 .Lsqb_exact
	s_cmpk_gt_i32 s24, 0x100
	s_cbranch_scc0 .Lsqb_s0lt
	s_mov_b32 s13, 0x80000001
	s_add_i32 s12, s19, 1
	s_mov_b32 s15, 0
	v_cvt_f32_u32_e32 v139, s24
	v_log_f32_e32 v139, v139
	v_mov_b32_e32 v141, 0x41100b88
	v_add_f32_e32 v139, 0xc1000b88, v139
	s_mov_b32 s22, 0
	s_mov_b32 s23, 0
	s_mov_b32 s21, 2
	s_branch .Lsqb_next

; __device__ __forceinline__ float keyval(unsigned k) { return __uint_as_float((k & 0x80000000u) ? (k ^ 0x80000000u) : ~k); }
; __device__ __forceinline__ unsigned valkey(float f) { const unsigned b = __float_as_uint(f); return b ^ ((unsigned)((int)b >> 31) | 0x80000000u); }
; __device__ __forceinline__ void select_query(const unsigned (&u)[64], unsigned vmax, int q, int b, int lane, unsigned* MASKb) {
;     ...
;                 unsigned vmin = 0xffffffffu;
; #pragma unroll
;                 for (int i = 0; i < 64; ++i) vmin = min(vmin, u[i] - 1u);
;                 lo = ~wave_umax(~vmin) + 1u; Llo = __log2f((float)n) - L256; hi = K0; Lhi = L256 - __log2f(fmaxf((float)c0, 0.5f));
;             }
;         }
;         int it = 0, last = 0;
;         while (!done) {
;             if (hi - lo <= 1u) { T = lo; exact = false; break; }
;             const float vlo = keyval(lo), vhi = keyval(hi);
;             const float frac = (it >= 9 && (it & 1)) ? 0.5f : Llo * __builtin_amdgcn_rcpf(Llo + Lhi);
;             unsigned mid = valkey(vlo + frac * (vhi - vlo));
;             if (mid <= lo) mid = lo + 1u;
;             if (mid >= hi) mid = hi - 1u;
;             mid = __builtin_amdgcn_readfirstlane(mid);
;             const int c = count_ge(u, mid, nblk);
;             if (c == 256) { T = mid; exact = true; break; }
;             if (c > 256) { lo = mid; Llo = __log2f((float)c) - L256; if (last == 1) Lhi *= 0.5f; last = 1; }
;             else { hi = mid; Lhi = L256 - __log2f(fmaxf((float)c, 0.5f)); if (last == 2) Llo *= 0.5f; last = 2; }
.Lsqb_s1lt:
	v_mov_b32_e32 v142, -1
	v_add_u32_e32 v138, -1, v98
	v_min_u32_e32 v142, v142, v138
	v_add_u32_e32 v138, -1, v107
	v_min_u32_e32 v142, v142, v138
	v_add_u32_e32 v138, -1, v99
	v_min_u32_e32 v142, v142, v138
	v_add_u32_e32 v138, -1, v108
	v_min_u32_e32 v142, v142, v138
	v_add_u32_e32 v138, -1, v109
	v_min_u32_e32 v142, v142, v138
	v_add_u32_e32 v138, -1, v113
	v_min_u32_e32 v142, v142, v138
	v_add_u32_e32 v138, -1, v110
	v_min_u32_e32 v142, v142, v138
	v_add_u32_e32 v138, -1, v114
	v_min_u32_e32 v142, v142, v138
	v_add_u32_e32 v138, -1, v111
	v_min_u32_e32 v142, v142, v138
	v_add_u32_e32 v138, -1, v115
	v_min_u32_e32 v142, v142, v138
	v_add_u32_e32 v138, -1, v112
	v_min_u32_e32 v142, v142, v138
	v_add_u32_e32 v138, -1, v116
	v_min_u32_e32 v142, v142, v138
	v_add_u32_e32 v138, -1, v117
	v_min_u32_e32 v142, v142, v138
	v_add_u32_e32 v138, -1, v119
	v_min_u32_e32 v142, v142, v138
	v_add_u32_e32 v138, -1, v118
	v_min_u32_e32 v142, v142, v138
	v_add_u32_e32 v138, -1, v121
	v_min_u32_e32 v142, v142, v138
	v_add_u32_e32 v138, -1, v120
	v_min_u32_e32 v142, v142, v138
	v_add_u32_e32 v138, -1, v123
	v_min_u32_e32 v142, v142, v138
	v_add_u32_e32 v138, -1, v122
	v_min_u32_e32 v142, v142, v138
	v_add_u32_e32 v138, -1, v124
	v_min_u32_e32 v142, v142, v138
	v_add_u32_e32 v138, -1, v125
	v_min_u32_e32 v142, v142, v138
	v_add_u32_e32 v138, -1, v127
	v_min_u32_e32 v142, v142, v138
	v_add_u32_e32 v138, -1, v126
	v_min_u32_e32 v142, v142, v138
	v_add_u32_e32 v138, -1, v128
	v_min_u32_e32 v142, v142, v138
	v_add_u32_e32 v138, -1, v129
	v_min_u32_e32 v142, v142, v138
	v_add_u32_e32 v138, -1, v131
	v_min_u32_e32 v142, v142, v138
	v_add_u32_e32 v138, -1, v130
	v_min_u32_e32 v142, v142, v138
	v_add_u32_e32 v138, -1, v132
	v_min_u32_e32 v142, v142, v138
	v_add_u32_e32 v138, -1, v133
	v_min_u32_e32 v142, v142, v138
	v_add_u32_e32 v138, -1, v134
	v_min_u32_e32 v142, v142, v138
	v_add_u32_e32 v138, -1, v136
	v_min_u32_e32 v142, v142, v138
	v_add_u32_e32 v138, -1, v137
	v_min_u32_e32 v142, v142, v138
	v_add_u32_e32 v138, -1, v46
	v_min_u32_e32 v142, v142, v138
	v_add_u32_e32 v138, -1, v48
	v_min_u32_e32 v142, v142, v138
	v_add_u32_e32 v138, -1, v47
	v_min_u32_e32 v142, v142, v138
	v_add_u32_e32 v138, -1, v49
	v_min_u32_e32 v142, v142, v138
	v_add_u32_e32 v138, -1, v42
	v_min_u32_e32 v142, v142, v138
	v_add_u32_e32 v138, -1, v50
	v_min_u32_e32 v142, v142, v138
	v_add_u32_e32 v138, -1, v43
	v_min_u32_e32 v142, v142, v138
	v_add_u32_e32 v138, -1, v44
	v_min_u32_e32 v142, v142, v138
	v_add_u32_e32 v138, -1, v38
	v_min_u32_e32 v142, v142, v138
	v_add_u32_e32 v138, -1, v45
	v_min_u32_e32 v142, v142, v138
	v_add_u32_e32 v138, -1, v39
	v_min_u32_e32 v142, v142, v138
	v_add_u32_e32 v138, -1, v40
	v_min_u32_e32 v142, v142, v138
	v_add_u32_e32 v138, -1, v41
	v_min_u32_e32 v142, v142, v138
	v_add_u32_e32 v138, -1, v52
	v_min_u32_e32 v142, v142, v138
	v_add_u32_e32 v138, -1, v51
	v_min_u32_e32 v142, v142, v138
	v_add_u32_e32 v138, -1, v54
	v_min_u32_e32 v142, v142, v138
	v_add_u32_e32 v138, -1, v53
	v_min_u32_e32 v142, v142, v138
	v_add_u32_e32 v138, -1, v56
	v_min_u32_e32 v142, v142, v138
	v_add_u32_e32 v138, -1, v55
	v_min_u32_e32 v142, v142, v138
	v_add_u32_e32 v138, -1, v57
	v_min_u32_e32 v142, v142, v138
	v_add_u32_e32 v138, -1, v58
	v_min_u32_e32 v142, v142, v138
	v_add_u32_e32 v138, -1, v60
	v_min_u32_e32 v142, v142, v138
	v_add_u32_e32 v138, -1, v59
	v_min_u32_e32 v142, v142, v138
	v_add_u32_e32 v138, -1, v61
	v_min_u32_e32 v142, v142, v138
	v_add_u32_e32 v138, -1, v62
	v_min_u32_e32 v142, v142, v138
	v_add_u32_e32 v138, -1, v64
	v_min_u32_e32 v142, v142, v138
	v_add_u32_e32 v138, -1, v63
	v_min_u32_e32 v142, v142, v138
	v_add_u32_e32 v138, -1, v65
	v_min_u32_e32 v142, v142, v138
	v_add_u32_e32 v138, -1, v72
	v_min_u32_e32 v142, v142, v138
	v_add_u32_e32 v138, -1, v73
	v_min_u32_e32 v142, v142, v138
	v_add_u32_e32 v138, -1, v74
	v_min_u32_e32 v142, v142, v138
	v_add_u32_e32 v138, -1, v75
	v_min_u32_e32 v142, v142, v138
	v_not_b32_e32 v142, v142
	s_nop 1
	v_max_u32_dpp v142, v142, v142 row_shr:1 row_mask:0xf bank_mask:0xf bound_ctrl:1
	s_nop 1
	v_max_u32_dpp v142, v142, v142 row_shr:2 row_mask:0xf bank_mask:0xf bound_ctrl:1
	s_nop 1
	v_max_u32_dpp v142, v142, v142 row_shr:4 row_mask:0xf bank_mask:0xf bound_ctrl:1
	s_nop 1
	v_max_u32_dpp v142, v142, v142 row_shr:8 row_mask:0xf bank_mask:0xf bound_ctrl:1
	s_nop 1
	v_max_u32_dpp v142, v142, v142 row_bcast:15 row_mask:0xa bank_mask:0xf
	s_nop 1
	v_max_u32_dpp v142, v142, v142 row_bcast:31 row_mask:0xc bank_mask:0xf
	s_nop 0
	v_readlane_b32 s26, v142, 63
	s_sub_i32 s13, 0, s26
	s_mov_b32 s12, 0x80000000
	s_mov_b32 s15, s24
	s_add_i32 s26, s75, 2
	v_cvt_f32_u32_e32 v139, s26
	v_log_f32_e32 v139, v139
	v_cvt_f32_u32_e32 v141, s24
	v_max_f32_e32 v141, 0.5, v141
	v_log_f32_e32 v141, v141
	v_add_f32_e32 v139, 0xc1000b88, v139
	v_sub_f32_e32 v141, 0x41000b88, v141
	s_mov_b32 s22, 0
	s_mov_b32 s23, 0
	s_mov_b32 s21, 2
	s_branch .Lsqb_next
.Lsqb_st2:
	s_cmpk_eq_i32 s24, 0x100
	s_cbranch_scc1 .Lsqb_exact
	s_cmpk_gt_i32 s24, 0x100
	s_cbranch_scc0 .Lsqb_s2lt
	s_mov_b32 s13, s14
	v_cvt_f32_u32_e32 v139, s24
	v_log_f32_e32 v139, v139
	s_cmp_lg_u32 s23, 1
	s_cbranch_scc1 .Lsqb_s2a
	v_mul_f32_e32 v141, 0.5, v141
.Lsqb_s2a:
	v_add_f32_e32 v139, 0xc1000b88, v139
	s_mov_b32 s23, 1
	s_add_i32 s22, s22, 1
	s_branch .Lsqb_next
.Lsqb_s2lt:
	s_mov_b32 s12, s14
	s_mov_b32 s15, s24
	v_cvt_f32_u32_e32 v141, s24
	v_max_f32_e32 v141, 0.5, v141
	v_log_f32_e32 v141, v141
	s_cmp_lg_u32 s23, 2
	s_cbranch_scc1 .Lsqb_s2b
	v_mul_f32_e32 v139, 0.5, v139
.Lsqb_s2b:
	v_sub_f32_e32 v141, 0x41000b88, v141
	s_mov_b32 s23, 2
	s_add_i32 s22, s22, 1
.Lsqb_next:
	s_sub_u32 s26, s12, s13
	s_cmp_lt_u32 s26, 2
	s_cbranch_scc1 .Lsqb_collapse
	s_cmp_gt_i32 s13, -1
	s_cselect_b32 s26, -1, 0x80000000
	s_xor_b32 s16, s13, s26
	s_cmp_gt_i32 s12, -1
	s_cselect_b32 s26, -1, 0x80000000
	s_xor_b32 s17, s12, s26
	s_cmp_lt_i32 s22, 9
	s_cbranch_scc1 .Lsqb_interp
	s_bitcmp1_b32 s22, 0
	s_cbranch_scc0 .Lsqb_interp
	v_mov_b32_e32 v142, 0.5
	s_branch .Lsqb_frac
.Lsqb_interp:
	v_add_f32_e32 v142, v139, v141
	v_rcp_f32_e32 v142, v142
	s_nop 0
	v_mul_f32_e32 v142, v139, v142
.Lsqb_frac:
	v_mov_b32_e32 v138, s16
	v_sub_f32_e32 v140, s17, v138
	v_fma_f32 v142, v142, v140, v138
	v_ashrrev_i32_e32 v138, 31, v142
	v_bitop3_b32 v142, v138, v142, s38 bitop3:0x36
	s_nop 0
	v_readfirstlane_b32 s14, v142
	s_add_i32 s26, s13, 1
	s_max_u32 s14, s14, s26
	s_add_i32 s26, s12, -1
	s_min_u32 s14, s14, s26
	s_branch .Lsqb_count

; __device__ __forceinline__ void select_query(const unsigned (&u)[64], unsigned vmax, int q, int b, int lane, unsigned* MASKb) {
;     ...
;         if (exact) TG = T - 1u; else { TG = T; rrem = 256 - count_ge(u, T + 1u, nblk); }
;     }
;     int tbase = 0;
; #pragma unroll
;     for (int B = 0; B < 2; ++B) {
;         if (B < nblk) {
;             unsigned w = 0u; const unsigned tgs = __builtin_amdgcn_readfirstlane(TG);
; #pragma unroll
;             for (int e = 31; e >= 3; e -= 4) BIT4(w, tgs, u[B * 32 + e], u[B * 32 + e - 1], u[B * 32 + e - 2], u[B * 32 + e - 3]);
;             if (rrem > 0) {
;                 int ec = 0;
; #pragma unroll
;                 for (int e = 0; e < 32; ++e) ec += (u[B * 32 + e] == T) ? 1 : 0;
.Lsqb_fin:
	v_mov_b32_e32 v76, s26
	v_mov_b32_e32 v77, s27
	v_mov_b32_e32 v69, s28
.Lsqb_done:
.LBB0_227:
	s_or_b64 exec, exec, s[8:9]
	v_mov_b32_e32 v79, 0
	v_cmp_lt_i32_e32 vcc, 0, v69
	v_cmp_lt_i32_e64 s[4:5], 0, v0
	s_and_saveexec_b64 s[72:73], s[4:5]
	s_cbranch_execz .LBB0_233
	v_mov_b32_e32 v78, 0
	v_readfirstlane_b32 s14, v77
	v_cmp_gt_u32_e64 s[4:5], v137, s14
	v_cmp_gt_u32_e64 s[6:7], v136, s14
	v_cmp_gt_u32_e64 s[8:9], v134, s14
	v_cmp_gt_u32_e64 s[10:11], v133, s14
	v_addc_co_u32_e64 v78, s[12:13], v78, v78, s[4:5]
	v_addc_co_u32_e64 v78, s[12:13], v78, v78, s[6:7]
	v_addc_co_u32_e64 v78, s[12:13], v78, v78, s[8:9]
	v_addc_co_u32_e64 v78, s[12:13], v78, v78, s[10:11]
	v_mov_b32_e32 v79, 0
	v_cmp_gt_u32_e64 s[4:5], v132, s14
	v_cmp_gt_u32_e64 s[6:7], v130, s14
	v_cmp_gt_u32_e64 s[8:9], v131, s14
	v_cmp_gt_u32_e64 s[10:11], v129, s14
	v_addc_co_u32_e64 v78, s[12:13], v78, v78, s[4:5]
	v_addc_co_u32_e64 v78, s[12:13], v78, v78, s[6:7]
	v_addc_co_u32_e64 v78, s[12:13], v78, v78, s[8:9]
	v_addc_co_u32_e64 v78, s[12:13], v78, v78, s[10:11]
	v_cmp_gt_u32_e64 s[4:5], v128, s14
	v_cmp_gt_u32_e64 s[6:7], v126, s14
	v_cmp_gt_u32_e64 s[8:9], v127, s14
	v_cmp_gt_u32_e64 s[10:11], v125, s14
	v_addc_co_u32_e64 v78, s[12:13], v78, v78, s[4:5]
	v_addc_co_u32_e64 v78, s[12:13], v78, v78, s[6:7]
	v_addc_co_u32_e64 v78, s[12:13], v78, v78, s[8:9]
	v_addc_co_u32_e64 v78, s[12:13], v78, v78, s[10:11]
	v_cmp_gt_u32_e64 s[4:5], v124, s14
	v_cmp_gt_u32_e64 s[6:7], v122, s14
	v_cmp_gt_u32_e64 s[8:9], v123, s14
	v_cmp_gt_u32_e64 s[10:11], v120, s14
	v_addc_co_u32_e64 v78, s[12:13], v78, v78, s[4:5]
	v_addc_co_u32_e64 v78, s[12:13], v78, v78, s[6:7]
	v_addc_co_u32_e64 v78, s[12:13], v78, v78, s[8:9]
	v_addc_co_u32_e64 v78, s[12:13], v78, v78, s[10:11]
	v_cmp_gt_u32_e64 s[4:5], v121, s14
	v_cmp_gt_u32_e64 s[6:7], v118, s14
	v_cmp_gt_u32_e64 s[8:9], v119, s14
	v_cmp_gt_u32_e64 s[10:11], v117, s14
	v_addc_co_u32_e64 v78, s[12:13], v78, v78, s[4:5]
	v_addc_co_u32_e64 v78, s[12:13], v78, v78, s[6:7]
	v_addc_co_u32_e64 v78, s[12:13], v78, v78, s[8:9]
	v_addc_co_u32_e64 v78, s[12:13], v78, v78, s[10:11]
	v_cmp_gt_u32_e64 s[4:5], v116, s14
	v_cmp_gt_u32_e64 s[6:7], v112, s14
	v_cmp_gt_u32_e64 s[8:9], v115, s14
	v_cmp_gt_u32_e64 s[10:11], v111, s14
	v_addc_co_u32_e64 v78, s[12:13], v78, v78, s[4:5]
	v_addc_co_u32_e64 v78, s[12:13], v78, v78, s[6:7]
	v_addc_co_u32_e64 v78, s[12:13], v78, v78, s[8:9]
	v_addc_co_u32_e64 v78, s[12:13], v78, v78, s[10:11]
	v_cmp_gt_u32_e64 s[4:5], v114, s14
	v_cmp_gt_u32_e64 s[6:7], v110, s14
	v_cmp_gt_u32_e64 s[8:9], v113, s14
	v_cmp_gt_u32_e64 s[10:11], v109, s14
	v_addc_co_u32_e64 v78, s[12:13], v78, v78, s[4:5]
	v_addc_co_u32_e64 v78, s[12:13], v78, v78, s[6:7]
	v_addc_co_u32_e64 v78, s[12:13], v78, v78, s[8:9]
	v_addc_co_u32_e64 v78, s[12:13], v78, v78, s[10:11]
	v_cmp_gt_u32_e64 s[4:5], v108, s14
	v_cmp_gt_u32_e64 s[6:7], v99, s14
	v_cmp_gt_u32_e64 s[8:9], v107, s14
	v_cmp_gt_u32_e64 s[10:11], v98, s14
	v_addc_co_u32_e64 v78, s[12:13], v78, v78, s[4:5]
	v_addc_co_u32_e64 v78, s[12:13], v78, v78, s[6:7]
	v_addc_co_u32_e64 v78, s[12:13], v78, v78, s[8:9]
	v_addc_co_u32_e64 v78, s[12:13], v78, v78, s[10:11]
	s_and_saveexec_b64 s[90:91], vcc
	s_cbranch_execz .LBB0_230
	v_cmp_eq_u32_e64 s[4:5], v137, v76
	v_cmp_eq_u32_e64 s[8:9], v136, v76
	v_cmp_eq_u32_e64 s[6:7], v134, v76
	v_cndmask_b32_e64 v95, 0, 1, s[4:5]
	v_addc_co_u32_e64 v95, s[12:13], 0, v95, s[8:9]
	v_cndmask_b32_e64 v94, 0, 1, s[6:7]
	v_cmp_eq_u32_e64 s[12:13], v133, v76
	v_cmp_eq_u32_e64 s[10:11], v132, v76
	v_cmp_eq_u32_e64 s[14:15], v131, v76
	v_addc_co_u32_e64 v94, s[18:19], v95, v94, s[12:13]
	v_cndmask_b32_e64 v93, 0, 1, s[10:11]
	v_cmp_eq_u32_e64 s[18:19], v130, v76
	v_cndmask_b32_e64 v92, 0, 1, s[14:15]
	v_cmp_eq_u32_e64 s[16:17], v128, v76
	v_addc_co_u32_e64 v93, s[24:25], v94, v93, s[18:19]
	v_cmp_eq_u32_e64 s[24:25], v129, v76
	v_cndmask_b32_e64 v91, 0, 1, s[16:17]
	v_cmp_eq_u32_e64 s[20:21], v127, v76
	v_addc_co_u32_e64 v92, s[28:29], v93, v92, s[24:25]
	v_cmp_eq_u32_e64 s[28:29], v126, v76
	v_cndmask_b32_e64 v90, 0, 1, s[20:21]
	v_cmp_eq_u32_e64 s[22:23], v124, v76
	v_addc_co_u32_e64 v91, s[36:37], v92, v91, s[28:29]
	v_cmp_eq_u32_e64 s[36:37], v125, v76
	v_cndmask_b32_e64 v89, 0, 1, s[22:23]
	v_cmp_eq_u32_e64 s[26:27], v123, v76
	v_addc_co_u32_e64 v90, s[42:43], v91, v90, s[36:37]
	v_cmp_eq_u32_e64 s[42:43], v122, v76
	v_cndmask_b32_e64 v87, 0, 1, s[26:27]
	v_cmp_eq_u32_e64 s[30:31], v121, v76
	v_addc_co_u32_e64 v89, s[48:49], v90, v89, s[42:43]
	v_cmp_eq_u32_e64 s[48:49], v120, v76
	v_cndmask_b32_e64 v86, 0, 1, s[30:31]
	v_cmp_eq_u32_e64 s[34:35], v119, v76
	v_addc_co_u32_e64 v87, s[52:53], v89, v87, s[48:49]
	v_cmp_eq_u32_e64 s[52:53], v118, v76
	v_cndmask_b32_e64 v85, 0, 1, s[34:35]
	s_mov_b32 s82, s38
	v_addc_co_u32_e64 v86, s[56:57], v87, v86, s[52:53]
	v_cmp_eq_u32_e64 s[56:57], v117, v76
	v_cmp_eq_u32_e64 s[38:39], v116, v76
	v_cmp_eq_u32_e64 s[40:41], v115, v76
	v_addc_co_u32_e64 v85, s[58:59], v86, v85, s[56:57]
	v_cndmask_b32_e64 v84, 0, 1, s[38:39]
	v_cmp_eq_u32_e64 s[58:59], v112, v76
	v_cndmask_b32_e64 v83, 0, 1, s[40:41]
	v_cmp_eq_u32_e64 s[44:45], v114, v76
	v_addc_co_u32_e64 v84, s[60:61], v85, v84, s[58:59]
	v_cmp_eq_u32_e64 s[60:61], v111, v76
	v_cndmask_b32_e64 v82, 0, 1, s[44:45]
	v_cmp_eq_u32_e64 s[46:47], v113, v76
	v_addc_co_u32_e64 v83, s[62:63], v84, v83, s[60:61]
	v_cmp_eq_u32_e64 s[62:63], v110, v76
	v_cndmask_b32_e64 v81, 0, 1, s[46:47]
	v_cmp_eq_u32_e64 s[50:51], v108, v76
	v_addc_co_u32_e64 v82, s[64:65], v83, v82, s[62:63]
	v_cmp_eq_u32_e64 s[64:65], v109, v76
	v_cndmask_b32_e64 v80, 0, 1, s[50:51]
	v_cmp_eq_u32_e64 s[54:55], v107, v76
	v_addc_co_u32_e64 v81, s[66:67], v82, v81, s[64:65]
	v_cmp_eq_u32_e64 s[66:67], v99, v76
	v_cndmask_b32_e64 v79, 0, 1, s[54:55]
	s_nop 0
	v_addc_co_u32_e64 v80, s[68:69], v81, v80, s[66:67]
	v_cmp_eq_u32_e64 s[68:69], v98, v76
	s_nop 1
	v_addc_co_u32_e64 v79, s[70:71], v80, v79, s[68:69]
	ds_bpermute_b32 v80, v100, v79
	v_cmp_lt_i32_e64 s[70:71], 0, v68
	s_waitcnt lgkmcnt(0)
; __device__ __forceinline__ void select_query(const unsigned (&u)[64], unsigned vmax, int q, int b, int lane, unsigned* MASKb) {
;     ...
;                 int incl = ec;
; #pragma unroll
;                 for (int o = 1; o < 64; o <<= 1) { const int t = __shfl_up(incl, o); if (lane >= o) incl += t; }
;                 const int total = __builtin_amdgcn_readlane(incl, 63);
;                 const int quota = rrem - tbase - (incl - ec);
;                 int taken = 0;
; #pragma unroll
;                 for (int e = 0; e < 32; ++e) { const bool is = (u[B * 32 + e] == T) && (taken < quota); w |= is ? (1u << e) : 0u; taken += is ? 1 : 0; }
	s_nop 0
	v_cndmask_b32_e64 v80, 0, v80, s[70:71]
	v_add_u32_e32 v80, v80, v79
	ds_bpermute_b32 v81, v101, v80
	v_cmp_lt_i32_e64 s[70:71], 1, v68
	v_add_u32_e32 v79, v79, v69
	s_waitcnt lgkmcnt(0)
	v_cndmask_b32_e64 v81, 0, v81, s[70:71]
	v_add_u32_e32 v80, v81, v80
	ds_bpermute_b32 v81, v102, v80
	v_cmp_lt_i32_e64 s[70:71], 3, v68
	s_waitcnt lgkmcnt(0)
	s_nop 0
	v_cndmask_b32_e64 v81, 0, v81, s[70:71]
	v_add_u32_e32 v80, v81, v80
	ds_bpermute_b32 v81, v103, v80
	v_cmp_lt_i32_e64 s[70:71], 7, v68
	s_waitcnt lgkmcnt(0)
	s_nop 0
	v_cndmask_b32_e64 v81, 0, v81, s[70:71]
	v_add_u32_e32 v80, v81, v80
	ds_bpermute_b32 v81, v104, v80
	v_cmp_lt_i32_e64 s[70:71], 15, v68
	s_waitcnt lgkmcnt(0)
	s_nop 0
	v_cndmask_b32_e64 v81, 0, v81, s[70:71]
	v_add_u32_e32 v80, v81, v80
	ds_bpermute_b32 v81, v105, v80
	v_cmp_lt_i32_e64 s[70:71], 31, v68
	s_waitcnt lgkmcnt(0)
	s_nop 0
	v_cndmask_b32_e64 v81, 0, v81, s[70:71]
	v_add_u32_e32 v80, v81, v80
	v_sub_u32_e32 v79, v79, v80
	v_cmp_lt_i32_e64 s[70:71], 0, v79
	s_and_b64 s[68:69], s[68:69], s[70:71]
	v_cndmask_b32_e64 v81, 0, 1, s[68:69]
	v_cmp_gt_i32_e64 s[68:69], v79, v81
	s_and_b64 s[54:55], s[54:55], s[68:69]
	v_cndmask_b32_e64 v82, 0, 2, s[54:55]
	v_cndmask_b32_e64 v83, 0, 1, s[54:55]
	v_addc_co_u32_e64 v84, s[54:55], 0, v81, s[54:55]
	v_cmp_lt_i32_e64 s[54:55], v84, v79
	s_and_b64 s[54:55], s[66:67], s[54:55]
	s_nop 0
	v_cndmask_b32_e64 v84, 0, 4, s[54:55]
	v_addc_co_u32_e64 v83, s[54:55], v83, v81, s[54:55]
	v_cmp_lt_i32_e64 s[54:55], v83, v79
	s_and_b64 s[50:51], s[50:51], s[54:55]
	v_cndmask_b32_e64 v85, 0, 8, s[50:51]
	v_cndmask_b32_e64 v86, 0, 1, s[50:51]
	v_addc_co_u32_e64 v87, s[50:51], 0, v83, s[50:51]
	v_cmp_lt_i32_e64 s[50:51], v87, v79
	s_and_b64 s[50:51], s[64:65], s[50:51]
	v_or3_b32 v82, v82, v84, v85
	v_cndmask_b32_e64 v89, 0, 16, s[50:51]
	v_cndmask_b32_e64 v90, 0, 1, s[50:51]
	v_addc_co_u32_e64 v83, s[50:51], v83, v86, s[50:51]
	v_cmp_lt_i32_e64 s[50:51], v83, v79
	s_and_b64 s[46:47], s[46:47], s[50:51]
	v_cndmask_b32_e64 v86, 0, 32, s[46:47]
	v_cndmask_b32_e64 v91, 0, 1, s[46:47]
	v_addc_co_u32_e64 v87, s[46:47], v87, v90, s[46:47]
	v_cmp_lt_i32_e64 s[46:47], v87, v79
	s_and_b64 s[46:47], s[62:63], s[46:47]
	v_or3_b32 v82, v82, v89, v86
	v_cndmask_b32_e64 v90, 0, 64, s[46:47]
	v_cndmask_b32_e64 v92, 0, 1, s[46:47]
	v_addc_co_u32_e64 v83, s[46:47], v83, v91, s[46:47]
	v_cmp_lt_i32_e64 s[46:47], v83, v79
	s_and_b64 s[44:45], s[44:45], s[46:47]
	v_mov_b32_e32 v91, 0x80
	v_cndmask_b32_e64 v91, 0, v91, s[44:45]
	v_cndmask_b32_e64 v93, 0, 1, s[44:45]
	v_addc_co_u32_e64 v87, s[44:45], v87, v92, s[44:45]
	v_cmp_lt_i32_e64 s[44:45], v87, v79
	s_and_b64 s[44:45], s[60:61], s[44:45]
	v_mov_b32_e32 v92, 0x100
	v_cndmask_b32_e64 v92, 0, v92, s[44:45]
	v_cndmask_b32_e64 v94, 0, 1, s[44:45]
	v_addc_co_u32_e64 v83, s[44:45], v83, v93, s[44:45]
	v_cmp_lt_i32_e64 s[44:45], v83, v79
	s_and_b64 s[40:41], s[40:41], s[44:45]
	v_mov_b32_e32 v93, 0x200
	v_cndmask_b32_e64 v93, 0, v93, s[40:41]
	v_cndmask_b32_e64 v95, 0, 1, s[40:41]
	v_addc_co_u32_e64 v87, s[40:41], v87, v94, s[40:41]
	v_cmp_lt_i32_e64 s[40:41], v87, v79
	s_and_b64 s[40:41], s[58:59], s[40:41]
	v_mov_b32_e32 v94, 0x400
	v_cndmask_b32_e64 v94, 0, v94, s[40:41]
	v_cndmask_b32_e64 v96, 0, 1, s[40:41]
	v_addc_co_u32_e64 v83, s[40:41], v83, v95, s[40:41]
	v_cmp_lt_i32_e64 s[40:41], v83, v79
	s_and_b64 s[38:39], s[38:39], s[40:41]
	v_mov_b32_e32 v95, 0x800
	v_cndmask_b32_e64 v95, 0, v95, s[38:39]
	v_cndmask_b32_e64 v97, 0, 1, s[38:39]
	v_addc_co_u32_e64 v87, s[38:39], v87, v96, s[38:39]
	v_cmp_lt_i32_e64 s[38:39], v87, v79
	s_and_b64 s[38:39], s[56:57], s[38:39]
	v_mov_b32_e32 v96, 0x1000
	v_cndmask_b32_e64 v96, 0, v96, s[38:39]
	v_cndmask_b32_e64 v98, 0, 1, s[38:39]
	v_addc_co_u32_e64 v83, s[38:39], v83, v97, s[38:39]
	v_cmp_lt_i32_e64 s[38:39], v83, v79
	s_and_b64 s[34:35], s[34:35], s[38:39]
	v_cndmask_b32_e64 v97, 0, v240, s[34:35]
	v_cndmask_b32_e64 v99, 0, 1, s[34:35]
	v_addc_co_u32_e64 v87, s[34:35], v87, v98, s[34:35]
	v_cmp_lt_i32_e64 s[34:35], v87, v79
	s_and_b64 s[34:35], s[52:53], s[34:35]
	v_mov_b32_e32 v98, 0x4000
	v_cndmask_b32_e64 v98, 0, v98, s[34:35]
	v_cndmask_b32_e64 v106, 0, 1, s[34:35]
	v_addc_co_u32_e64 v83, s[34:35], v83, v99, s[34:35]
	v_cmp_lt_i32_e64 s[34:35], v83, v79
	s_and_b64 s[30:31], s[30:31], s[34:35]
	v_mov_b32_e32 v99, 0x8000
; __device__ __forceinline__ void select_query(const unsigned (&u)[64], unsigned vmax, int q, int b, int lane, unsigned* MASKb) {
;     ...
;                 const int quota = rrem - tbase - (incl - ec);
;                 int taken = 0;
; #pragma unroll
;                 for (int e = 0; e < 32; ++e) { const bool is = (u[B * 32 + e] == T) && (taken < quota); w |= is ? (1u << e) : 0u; taken += is ? 1 : 0; }
;                 tbase += total;
;             }
;             if (64 * B + lane <= (q >> 5)) __hip_atomic_store(MASKb + ((size_t)(b * 128 + (q >> 5)) * 128 + 64 * B + lane) * 32 + (q & 31), w, __ATOMIC_RELAXED, __HIP_MEMORY_SCOPE_AGENT);
	v_cndmask_b32_e64 v99, 0, v99, s[30:31]
	v_cndmask_b32_e64 v107, 0, 1, s[30:31]
	v_addc_co_u32_e64 v87, s[30:31], v87, v106, s[30:31]
	v_cmp_lt_i32_e64 s[30:31], v87, v79
	s_and_b64 s[30:31], s[48:49], s[30:31]
	v_mov_b32_e32 v106, 0x10000
	v_cndmask_b32_e64 v106, 0, v106, s[30:31]
	v_cndmask_b32_e64 v108, 0, 1, s[30:31]
	v_addc_co_u32_e64 v83, s[30:31], v83, v107, s[30:31]
	v_cmp_lt_i32_e64 s[30:31], v83, v79
	s_and_b64 s[26:27], s[26:27], s[30:31]
	v_mov_b32_e32 v107, 0x20000
	v_cndmask_b32_e64 v107, 0, v107, s[26:27]
	v_cndmask_b32_e64 v109, 0, 1, s[26:27]
	v_addc_co_u32_e64 v87, s[26:27], v87, v108, s[26:27]
	v_cmp_lt_i32_e64 s[26:27], v87, v79
	s_and_b64 s[26:27], s[42:43], s[26:27]
	v_mov_b32_e32 v108, 0x40000
	v_cndmask_b32_e64 v108, 0, v108, s[26:27]
	v_cndmask_b32_e64 v110, 0, 1, s[26:27]
	v_addc_co_u32_e64 v83, s[26:27], v83, v109, s[26:27]
	v_cmp_lt_i32_e64 s[26:27], v83, v79
	s_and_b64 s[22:23], s[22:23], s[26:27]
	v_mov_b32_e32 v109, 0x80000
	v_cndmask_b32_e64 v109, 0, v109, s[22:23]
	v_cndmask_b32_e64 v111, 0, 1, s[22:23]
	v_addc_co_u32_e64 v87, s[22:23], v87, v110, s[22:23]
	v_cmp_lt_i32_e64 s[22:23], v87, v79
	s_and_b64 s[22:23], s[36:37], s[22:23]
	v_mov_b32_e32 v110, 0x100000
	v_cndmask_b32_e64 v110, 0, v110, s[22:23]
	v_cndmask_b32_e64 v112, 0, 1, s[22:23]
	v_addc_co_u32_e64 v83, s[22:23], v83, v111, s[22:23]
	v_cmp_lt_i32_e64 s[22:23], v83, v79
	s_and_b64 s[20:21], s[20:21], s[22:23]
	v_mov_b32_e32 v111, 0x200000
	v_cndmask_b32_e64 v111, 0, v111, s[20:21]
	v_cndmask_b32_e64 v113, 0, 1, s[20:21]
	v_addc_co_u32_e64 v87, s[20:21], v87, v112, s[20:21]
	v_cmp_lt_i32_e64 s[20:21], v87, v79
	s_and_b64 s[20:21], s[28:29], s[20:21]
	v_mov_b32_e32 v112, 0x400000
	v_cndmask_b32_e64 v112, 0, v112, s[20:21]
	v_cndmask_b32_e64 v114, 0, 1, s[20:21]
	v_addc_co_u32_e64 v83, s[20:21], v83, v113, s[20:21]
	v_cmp_lt_i32_e64 s[20:21], v83, v79
	s_and_b64 s[16:17], s[16:17], s[20:21]
	v_mov_b32_e32 v113, 0x800000
	v_cndmask_b32_e64 v113, 0, v113, s[16:17]
	v_cndmask_b32_e64 v115, 0, 1, s[16:17]
	v_addc_co_u32_e64 v87, s[16:17], v87, v114, s[16:17]
	v_cmp_lt_i32_e64 s[16:17], v87, v79
	s_and_b64 s[16:17], s[24:25], s[16:17]
	v_mov_b32_e32 v114, 0x1000000
	v_cndmask_b32_e64 v114, 0, v114, s[16:17]
	v_cndmask_b32_e64 v116, 0, 1, s[16:17]
	v_addc_co_u32_e64 v83, s[16:17], v83, v115, s[16:17]
	v_cmp_lt_i32_e64 s[16:17], v83, v79
	s_and_b64 s[14:15], s[14:15], s[16:17]
	v_bfrev_b32_e32 v115, 64
	v_cndmask_b32_e64 v115, 0, v115, s[14:15]
	v_cndmask_b32_e64 v117, 0, 1, s[14:15]
	v_addc_co_u32_e64 v87, s[14:15], v87, v116, s[14:15]
	v_cmp_lt_i32_e64 s[14:15], v87, v79
	s_and_b64 s[14:15], s[18:19], s[14:15]
	v_bfrev_b32_e32 v116, 32
	v_cndmask_b32_e64 v116, 0, v116, s[14:15]
	v_cndmask_b32_e64 v118, 0, 1, s[14:15]
	v_addc_co_u32_e64 v83, s[14:15], v83, v117, s[14:15]
	v_cmp_lt_i32_e64 s[14:15], v83, v79
	s_and_b64 s[10:11], s[10:11], s[14:15]
	v_bfrev_b32_e32 v117, 16
	v_cndmask_b32_e64 v117, 0, v117, s[10:11]
	v_cndmask_b32_e64 v119, 0, 1, s[10:11]
	v_addc_co_u32_e64 v87, s[10:11], v87, v118, s[10:11]
	v_cmp_lt_i32_e64 s[10:11], v87, v79
	v_or3_b32 v82, v82, v90, v91
	s_and_b64 s[10:11], s[12:13], s[10:11]
	v_bfrev_b32_e32 v118, 8
	v_or3_b32 v82, v82, v92, v93
	v_cndmask_b32_e64 v118, 0, v118, s[10:11]
	v_cndmask_b32_e64 v120, 0, 1, s[10:11]
	v_addc_co_u32_e64 v83, s[10:11], v83, v119, s[10:11]
	v_or3_b32 v82, v82, v94, v95
	v_cmp_lt_i32_e64 s[10:11], v83, v79
	v_or3_b32 v82, v82, v96, v97
	s_and_b64 s[6:7], s[6:7], s[10:11]
	v_bfrev_b32_e32 v119, 4
	v_or3_b32 v82, v82, v98, v99
	v_cndmask_b32_e64 v119, 0, v119, s[6:7]
	v_cndmask_b32_e64 v121, 0, 1, s[6:7]
	v_addc_co_u32_e64 v87, s[6:7], v87, v120, s[6:7]
	v_or3_b32 v82, v82, v106, v107
	v_cmp_lt_i32_e64 s[6:7], v87, v79
	v_or3_b32 v82, v82, v108, v109
	s_and_b64 s[6:7], s[8:9], s[6:7]
	v_or3_b32 v82, v82, v110, v111
	v_cndmask_b32_e64 v87, 0, 2.0, s[6:7]
	v_addc_co_u32_e64 v83, s[6:7], v83, v121, s[6:7]
	v_or3_b32 v82, v82, v112, v113
	v_cmp_lt_i32_e64 s[6:7], v83, v79
	v_or3_b32 v82, v82, v114, v115
	s_and_b64 s[4:5], s[4:5], s[6:7]
	v_bfrev_b32_e32 v79, 1
	v_or3_b32 v82, v82, v116, v117
	v_cndmask_b32_e64 v79, 0, v79, s[4:5]
	v_or3_b32 v82, v82, v118, v119
	v_or3_b32 v79, v82, v87, v79
	v_readlane_b32 s4, v80, 63
	s_mov_b32 s38, s82
	v_or3_b32 v78, v79, v81, v78
	v_mov_b32_e32 v79, s4

; __device__ __forceinline__ void select_phase(const bf16_t* Z, const bf16_t* KIb, unsigned* MASKb, unsigned* itemcnt, LAS unsigned char* lds, int wave_in, int lane_in, int bid, int G, int sub) {
;     ...
;             asm volatile("s_waitcnt vmcnt(0)" ::: "memory");
;             if (lane == 0) __hip_atomic_fetch_add(itemcnt + idx, 1u, __ATOMIC_RELAXED, __HIP_MEMORY_SCOPE_AGENT);
; __device__ __forceinline__ void mixer_a(const bf16_t* __restrict__ Z, bf16_t* __restrict__ Y, const float* __restrict__ wc, int gtid, int NGT) {
; #pragma unroll 2
;     for (int it = gtid; it < MTOK * 32; it += NGT) {
;         const int row = it >> 5, c8 = (it & 31) * 8, pos = row & (SEQ - 1);
;         const bf16_t* zr = Z + (size_t)row * NZ;
.LBB0_238:
	s_or_b64 exec, exec, s[70:71]
	s_waitcnt vmcnt(0)
	v_cmp_eq_u32_e32 vcc, 0, v68
	s_and_saveexec_b64 s[4:5], vcc
	s_cbranch_execz .LBB0_114
	s_mov_b64 s[6:7], exec
	v_mbcnt_lo_u32_b32 v0, s6, 0
	v_mbcnt_hi_u32_b32 v0, s7, v0
	v_cmp_eq_u32_e32 vcc, 0, v0
	s_and_b64 s[8:9], exec, vcc
	s_mov_b64 exec, s[8:9]
	s_cbranch_execz .LBB0_114
	s_ashr_i32 s75, s74, 31
	s_lshl_b64 s[8:9], s[74:75], 2
	s_add_u32 s8, s80, s8
	s_addc_u32 s9, s84, s9
	s_bcnt1_i32_b64 s6, s[6:7]
	v_mov_b32_e32 v0, s6
	global_atomic_add v1, v0, s[8:9]
	s_branch .LBB0_114
.LBB0_243:
	s_waitcnt vmcnt(4)
	v_lshl_add_u32 v2, s76, 9, v247
	s_mov_b32 s4, 0x80000
	v_cmp_gt_i32_e32 vcc, s4, v2
	s_barrier
	s_and_saveexec_b64 s[4:5], vcc
	v_readlane_b32 s14, v255, 30
	v_readlane_b32 s15, v255, 31
	s_cbranch_execz .LBB0_246
	v_readlane_b32 s6, v255, 22
	v_readlane_b32 s7, v255, 23
	s_load_dwordx2 s[6:7], s[6:7], 0x18
	v_readlane_b32 s8, v255, 28
	v_readlane_b32 s9, v255, 29
	s_mulk_i32 s8, 0x300
	s_ashr_i32 s9, s8, 31
	s_lshl_b64 s[8:9], s[8:9], 2
	s_waitcnt lgkmcnt(0)
	s_add_u32 s6, s6, s8
	s_addc_u32 s7, s7, s9
	s_lshl_b32 s10, s97, 9
	v_lshlrev_b32_e32 v3, 3, v2
	s_lshl_b32 s11, s97, 12
	s_mov_b64 s[8:9], 0
